# v37 + residual-stream loads of the three residual GEMM epilogues software-pipelined two rows ahead (was 32 serial load-wait-store round trips)
# baseline (speedup 1.0000x reference)
; __device__ __forceinline__ unsigned cvt_pk_bf16(float lo, float hi) { unsigned r; asm volatile("v_cvt_pk_bf16_f32 %0, %1, %2" : "=v"(r) : "v"(lo), "v"(hi)); return r; }
; __device__ __forceinline__ float shx(float v, int o, int lane) { return __int_as_float(__builtin_amdgcn_ds_bpermute((lane ^ o) << 2, __float_as_int(v))); }
;     __device__ __forceinline__ void operator()(const f32x4 (&acc)[2][2][4][2], const Unit& u, int wr, int wc, int fr, int fq) const {
;         const int bidx = u.pm >> 4, row0 = u.pm * BM + wr * 64 + fr, col0 = u.pn * BM + wc * 32 + 4 * fq, lane = fq * 16 + fr;
;         f32x4 gv[2][2], gs[2][2];
; #pragma unroll
;         for (int bj = 0; bj < 2; ++bj)
; #pragma unroll
;             for (int n = 0; n < 2; ++n) { const int c = col0 + bj * HALF + n * 16; gv[bj][n] = *(const f32x4*)(gate + (size_t)bidx * NMOD + c);
;                 gs[bj][n] = *(const f32x4*)(gnext + c) * (*(const f32x4*)(scn + (size_t)bidx * NMOD + c) + 1.0f); }
; #pragma unroll
;         for (int ai = 0; ai < 2; ++ai)
; #pragma unroll
;             for (int m = 0; m < 4; ++m) { const int row = row0 + ai * HALF + m * 16; const size_t off = (size_t)row * DM + col0; float ss = 0.f;
; #pragma unroll
;                 for (int bj = 0; bj < 2; ++bj)
; #pragma unroll
;                     for (int n = 0; n < 2; ++n) { const f32x4 x = *(const f32x4*)(src + off + bj * HALF + n * 16) + gv[bj][n] * acc[ai][bj][m][n];
;                         *(f32x4*)(dst + off + bj * HALF + n * 16) = x; ss += (x[0] * x[0] + x[1] * x[1]) + (x[2] * x[2] + x[3] * x[3]);
;                         const f32x4 hh = x * gs[bj][n]; u32x2 w; w.x = cvt_pk_bf16(hh[0], hh[1]); w.y = cvt_pk_bf16(hh[2], hh[3]); *(u32x2*)(Hn + off + bj * HALF + n * 16) = w; }
;                 ss += shx(ss, 16, lane); ss += shx(ss, 32, lane);
;                 if (fq == 0) scr[(ai * HALF + wr * 64 + m * 16 + fr) * 4 + wc] = ss; }
.LBB0_536:
	s_ashr_i32 s25, s34, 4
	s_lshl_b32 s34, s34, 8
	s_mul_hi_i32 s27, s25, 0x6000
	s_mulk_i32 s25, 0x6000
	v_lshl_or_b32 v168, s36, 8, v185
	s_add_u32 s36, s57, s25
	s_addc_u32 s37, s58, s27
	s_add_u32 s38, s59, s25
	v_ashrrev_i32_e32 v169, 31, v168
	s_addc_u32 s39, s60, s27
	v_lshlrev_b64 v[76:77], 2, v[168:169]
	v_lshl_add_u64 v[176:177], s[38:39], 0, v[76:77]
	v_lshl_add_u64 v[170:171], s[36:37], 0, v[76:77]
	v_lshl_add_u64 v[174:175], s[20:21], 0, v[76:77]
	global_load_dwordx4 v[76:79], v[176:177], off
	global_load_dwordx4 v[72:75], v[174:175], off
	global_load_dwordx4 v[88:91], v[170:171], off
	s_waitcnt vmcnt(0)
	v_pk_add_f32 v[78:79], v[78:79], 1.0 op_sel_hi:[1,0]
	v_pk_add_f32 v[76:77], v[76:77], 1.0 op_sel_hi:[1,0]
	v_pk_mul_f32 v[164:165], v[74:75], v[78:79]
	v_pk_mul_f32 v[166:167], v[72:73], v[76:77]
	global_load_dwordx4 v[92:95], v[170:171], off offset:64
	global_load_dwordx4 v[72:75], v[174:175], off offset:64
	global_load_dwordx4 v[76:79], v[176:177], off offset:64
	s_waitcnt vmcnt(0)
	v_pk_add_f32 v[78:79], v[78:79], 1.0 op_sel_hi:[1,0]
	v_pk_add_f32 v[76:77], v[76:77], 1.0 op_sel_hi:[1,0]
	v_pk_mul_f32 v[160:161], v[74:75], v[78:79]
	v_pk_mul_f32 v[162:163], v[72:73], v[76:77]
	global_load_dwordx4 v[76:79], v[170:171], off offset:512
	global_load_dwordx4 v[72:75], v[174:175], off offset:512
	global_load_dwordx4 v[152:155], v[176:177], off offset:512
	s_waitcnt vmcnt(0)
	v_pk_add_f32 v[154:155], v[154:155], 1.0 op_sel_hi:[1,0]
	v_pk_add_f32 v[152:153], v[152:153], 1.0 op_sel_hi:[1,0]
	v_pk_mul_f32 v[156:157], v[74:75], v[154:155]
	v_pk_mul_f32 v[158:159], v[72:73], v[152:153]
	global_load_dwordx4 v[72:75], v[170:171], off offset:576
	global_load_dwordx4 v[152:155], v[174:175], off offset:576
	s_nop 0
	global_load_dwordx4 v[174:177], v[176:177], off offset:576
	s_waitcnt vmcnt(0)
	v_pk_add_f32 v[170:171], v[176:177], 1.0 op_sel_hi:[1,0]
	s_nop 0
	v_pk_mul_f32 v[154:155], v[154:155], v[170:171]
	v_add_u32_e32 v170, s34, v180
	v_pk_add_f32 v[174:175], v[174:175], 1.0 op_sel_hi:[1,0]
	v_ashrrev_i32_e32 v171, 31, v170
	v_pk_mul_f32 v[152:153], v[152:153], v[174:175]
	v_lshlrev_b64 v[174:175], 10, v[170:171]
	v_lshl_add_u64 v[192:193], v[174:175], 0, v[168:169]
	v_lshlrev_b64 v[194:195], 2, v[192:193]
	v_lshl_add_u64 v[178:179], s[4:5], 0, v[194:195]
	v_mov_b32_e32 v228, v194
	v_mov_b32_e32 v229, v228
	global_load_dwordx4 v[196:199], v229, s[4:5]
	global_load_dwordx4 v[200:203], v229, s[4:5] offset:64
	global_load_dwordx4 v[204:207], v229, s[4:5] offset:512
	global_load_dwordx4 v[208:211], v229, s[4:5] offset:576
	v_add_u32_e32 v229, 0x10000, v228
	global_load_dwordx4 v[212:215], v229, s[4:5]
	global_load_dwordx4 v[216:219], v229, s[4:5] offset:64
	global_load_dwordx4 v[220:223], v229, s[4:5] offset:512
	global_load_dwordx4 v[224:227], v229, s[4:5] offset:576
	s_waitcnt vmcnt(7)
	v_pk_fma_f32 v[176:177], v[142:143], v[90:91], v[198:199]
	v_pk_fma_f32 v[174:175], v[140:141], v[88:89], v[196:197]
	v_mul_f32_e32 v143, v177, v177
	v_mul_f32_e32 v142, v175, v175
	v_lshl_add_u64 v[140:141], s[12:13], 0, v[194:195]
	v_fmac_f32_e32 v142, v174, v174
	v_fmac_f32_e32 v143, v176, v176
	global_store_dwordx4 v[140:141], v[174:177], off
	v_add_f32_e32 v194, v142, v143
	v_pk_mul_f32 v[142:143], v[164:165], v[176:177]
	v_pk_mul_f32 v[174:175], v[166:167], v[174:175]
	s_nop 0
	v_cvt_pk_bf16_f32 v174, v174, v175
	v_cvt_pk_bf16_f32 v175, v142, v143
	v_lshl_add_u64 v[142:143], v[192:193], 1, s[18:19]
	global_store_dwordx2 v[142:143], v[174:175], off
	s_waitcnt vmcnt(8)
	v_pk_fma_f32 v[136:137], v[136:137], v[92:93], v[200:201]
	v_pk_fma_f32 v[138:139], v[138:139], v[94:95], v[202:203]
	v_mul_f32_e32 v174, v137, v137
	global_store_dwordx4 v[140:141], v[136:139], off offset:64
	v_fmac_f32_e32 v174, v136, v136
	v_mul_f32_e32 v175, v139, v139
	v_pk_mul_f32 v[136:137], v[162:163], v[136:137]
	v_fmac_f32_e32 v175, v138, v138
	v_pk_mul_f32 v[138:139], v[160:161], v[138:139]
	v_cvt_pk_bf16_f32 v136, v136, v137
	v_add_f32_e32 v174, v174, v175
	v_cvt_pk_bf16_f32 v137, v138, v139
	global_store_dwordx2 v[142:143], v[136:137], off offset:32
	v_add_f32_e32 v174, v194, v174
	s_waitcnt vmcnt(9)
	v_pk_fma_f32 v[132:133], v[132:133], v[76:77], v[204:205]
	v_pk_fma_f32 v[134:135], v[134:135], v[78:79], v[206:207]
	v_mul_f32_e32 v136, v133, v133
	global_store_dwordx4 v[140:141], v[132:135], off offset:512
	v_fmac_f32_e32 v136, v132, v132
	v_mul_f32_e32 v137, v135, v135
	v_pk_mul_f32 v[132:133], v[158:159], v[132:133]
	v_fmac_f32_e32 v137, v134, v134
	v_pk_mul_f32 v[134:135], v[156:157], v[134:135]
	v_cvt_pk_bf16_f32 v132, v132, v133
	v_add_f32_e32 v136, v136, v137
	v_cvt_pk_bf16_f32 v133, v134, v135
	global_store_dwordx2 v[142:143], v[132:133], off offset:256
	v_add_f32_e32 v136, v174, v136
	s_waitcnt vmcnt(10)
	v_pk_fma_f32 v[130:131], v[130:131], v[74:75], v[210:211]
	v_pk_fma_f32 v[128:129], v[128:129], v[72:73], v[208:209]
	v_add_u32_e32 v229, 0x20000, v228
	global_load_dwordx4 v[196:199], v229, s[4:5]
	global_load_dwordx4 v[200:203], v229, s[4:5] offset:64
	global_load_dwordx4 v[204:207], v229, s[4:5] offset:512
	global_load_dwordx4 v[208:211], v229, s[4:5] offset:576
	v_mul_f32_e32 v133, v131, v131
	v_mul_f32_e32 v132, v129, v129
	v_fmac_f32_e32 v132, v128, v128
	v_fmac_f32_e32 v133, v130, v130
	global_store_dwordx4 v[140:141], v[128:131], off offset:576
	v_add_f32_e32 v132, v132, v133
	v_add_f32_e32 v132, v136, v132
	v_pk_mul_f32 v[128:129], v[152:153], v[128:129]
	v_pk_mul_f32 v[130:131], v[154:155], v[130:131]
	v_cvt_pk_bf16_f32 v128, v128, v129
	s_nop 0
	v_cvt_pk_bf16_f32 v129, v130, v131
	global_store_dwordx2 v[142:143], v[128:129], off offset:288
	ds_bpermute_b32 v128, v182, v132
	s_waitcnt lgkmcnt(0)
	v_add_f32_e32 v128, v132, v128
	ds_bpermute_b32 v129, v183, v128
	s_and_saveexec_b64 s[36:37], s[6:7]
	s_cbranch_execz .LBB0_538
	s_waitcnt lgkmcnt(0)
	v_add_f32_e32 v128, v128, v129
	ds_write_b32 v184, v128
; __device__ __forceinline__ unsigned cvt_pk_bf16(float lo, float hi) { unsigned r; asm volatile("v_cvt_pk_bf16_f32 %0, %1, %2" : "=v"(r) : "v"(lo), "v"(hi)); return r; }
; __device__ __forceinline__ float shx(float v, int o, int lane) { return __int_as_float(__builtin_amdgcn_ds_bpermute((lane ^ o) << 2, __float_as_int(v))); }
;     __device__ __forceinline__ void operator()(const f32x4 (&acc)[2][2][4][2], const Unit& u, int wr, int wc, int fr, int fq) const {
;     ...
;             for (int m = 0; m < 4; ++m) { const int row = row0 + ai * HALF + m * 16; const size_t off = (size_t)row * DM + col0; float ss = 0.f;
; #pragma unroll
;                 for (int bj = 0; bj < 2; ++bj)
; #pragma unroll
;                     for (int n = 0; n < 2; ++n) { const f32x4 x = *(const f32x4*)(src + off + bj * HALF + n * 16) + gv[bj][n] * acc[ai][bj][m][n];
;                         *(f32x4*)(dst + off + bj * HALF + n * 16) = x; ss += (x[0] * x[0] + x[1] * x[1]) + (x[2] * x[2] + x[3] * x[3]);
;                         const f32x4 hh = x * gs[bj][n]; u32x2 w; w.x = cvt_pk_bf16(hh[0], hh[1]); w.y = cvt_pk_bf16(hh[2], hh[3]); *(u32x2*)(Hn + off + bj * HALF + n * 16) = w; }
;                 ss += shx(ss, 16, lane); ss += shx(ss, 32, lane);
;                 if (fq == 0) scr[(ai * HALF + wr * 64 + m * 16 + fr) * 4 + wc] = ss; }
.LBB0_538:
	s_or_b64 exec, exec, s[36:37]
	v_or_b32_e32 v128, 16, v170
	s_waitcnt lgkmcnt(0)
	v_ashrrev_i32_e32 v129, 31, v128
	v_lshlrev_b64 v[128:129], 10, v[128:129]
	v_lshl_add_u64 v[132:133], v[128:129], 0, v[168:169]
	v_lshlrev_b64 v[134:135], 2, v[132:133]
	v_lshl_add_u64 v[136:137], s[4:5], 0, v[134:135]
	v_lshl_add_u64 v[132:133], v[132:133], 1, s[18:19]
	v_lshl_add_u64 v[134:135], s[12:13], 0, v[134:135]
	s_waitcnt vmcnt(15)
	v_pk_fma_f32 v[124:125], v[124:125], v[88:89], v[212:213]
	v_pk_fma_f32 v[126:127], v[126:127], v[90:91], v[214:215]
	v_pk_mul_f32 v[130:131], v[166:167], v[124:125]
	global_store_dwordx4 v[134:135], v[124:127], off
	v_pk_mul_f32 v[128:129], v[164:165], v[126:127]
	v_cvt_pk_bf16_f32 v130, v130, v131
	s_nop 0
	v_cvt_pk_bf16_f32 v131, v128, v129
	global_store_dwordx2 v[132:133], v[130:131], off
	v_mul_f32_e32 v125, v125, v125
	v_mul_f32_e32 v127, v127, v127
	v_fmac_f32_e32 v125, v124, v124
	v_fmac_f32_e32 v127, v126, v126
	v_add_f32_e32 v124, v125, v127
	s_waitcnt vmcnt(16)
	v_pk_fma_f32 v[120:121], v[120:121], v[92:93], v[216:217]
	v_pk_fma_f32 v[122:123], v[122:123], v[94:95], v[218:219]
	v_pk_mul_f32 v[130:131], v[162:163], v[120:121]
	global_store_dwordx4 v[134:135], v[120:123], off offset:64
	v_pk_mul_f32 v[128:129], v[160:161], v[122:123]
	v_cvt_pk_bf16_f32 v130, v130, v131
	s_nop 0
	v_cvt_pk_bf16_f32 v131, v128, v129
	global_store_dwordx2 v[132:133], v[130:131], off offset:32
	v_mul_f32_e32 v121, v121, v121
	v_mul_f32_e32 v123, v123, v123
	v_fmac_f32_e32 v121, v120, v120
	v_fmac_f32_e32 v123, v122, v122
	v_add_f32_e32 v120, v121, v123
	v_add_f32_e32 v120, v124, v120
	s_waitcnt vmcnt(17)
	v_pk_fma_f32 v[116:117], v[116:117], v[76:77], v[220:221]
	v_pk_fma_f32 v[118:119], v[118:119], v[78:79], v[222:223]
	v_pk_mul_f32 v[130:131], v[158:159], v[116:117]
	global_store_dwordx4 v[134:135], v[116:119], off offset:512
	v_pk_mul_f32 v[128:129], v[156:157], v[118:119]
	v_cvt_pk_bf16_f32 v130, v130, v131
	s_nop 0
	v_cvt_pk_bf16_f32 v131, v128, v129
	global_store_dwordx2 v[132:133], v[130:131], off offset:256
	v_mul_f32_e32 v117, v117, v117
	v_mul_f32_e32 v119, v119, v119
	v_fmac_f32_e32 v117, v116, v116
	v_fmac_f32_e32 v119, v118, v118
	v_add_f32_e32 v116, v117, v119
	v_add_f32_e32 v118, v120, v116
	s_waitcnt vmcnt(18)
	v_pk_fma_f32 v[116:117], v[114:115], v[74:75], v[226:227]
	v_pk_fma_f32 v[114:115], v[112:113], v[72:73], v[224:225]
	v_add_u32_e32 v229, 0x30000, v228
	global_load_dwordx4 v[212:215], v229, s[4:5]
	global_load_dwordx4 v[216:219], v229, s[4:5] offset:64
	global_load_dwordx4 v[220:223], v229, s[4:5] offset:512
	global_load_dwordx4 v[224:227], v229, s[4:5] offset:576
	v_mul_f32_e32 v113, v117, v117
	v_mul_f32_e32 v112, v115, v115
	v_fmac_f32_e32 v112, v114, v114
	v_fmac_f32_e32 v113, v116, v116
	v_add_f32_e32 v112, v112, v113
	v_add_f32_e32 v112, v118, v112
	ds_bpermute_b32 v113, v182, v112
	global_store_dwordx4 v[134:135], v[114:117], off offset:576
	s_waitcnt lgkmcnt(0)
	v_add_f32_e32 v112, v112, v113
	ds_bpermute_b32 v113, v183, v112
	v_pk_mul_f32 v[114:115], v[152:153], v[114:115]
	v_pk_mul_f32 v[116:117], v[154:155], v[116:117]
	v_cvt_pk_bf16_f32 v114, v114, v115
	s_nop 0
	v_cvt_pk_bf16_f32 v115, v116, v117
	global_store_dwordx2 v[132:133], v[114:115], off offset:288
	s_and_saveexec_b64 s[36:37], s[6:7]
	s_cbranch_execz .LBB0_540
	s_waitcnt lgkmcnt(0)
	v_add_f32_e32 v112, v112, v113
	ds_write_b32 v184, v112 offset:256
.LBB0_540:
	s_or_b64 exec, exec, s[36:37]
	v_or_b32_e32 v112, 32, v170
	s_waitcnt lgkmcnt(0)
	v_ashrrev_i32_e32 v113, 31, v112
	v_lshlrev_b64 v[112:113], 10, v[112:113]
	v_lshl_add_u64 v[116:117], v[112:113], 0, v[168:169]
	v_lshlrev_b64 v[118:119], 2, v[116:117]
	v_lshl_add_u64 v[120:121], s[4:5], 0, v[118:119]
	v_lshl_add_u64 v[116:117], v[116:117], 1, s[18:19]
	v_lshl_add_u64 v[118:119], s[12:13], 0, v[118:119]
	s_waitcnt vmcnt(17)
	v_pk_fma_f32 v[108:109], v[108:109], v[88:89], v[196:197]
	v_pk_fma_f32 v[110:111], v[110:111], v[90:91], v[198:199]
	v_pk_mul_f32 v[114:115], v[166:167], v[108:109]
	global_store_dwordx4 v[118:119], v[108:111], off
	v_pk_mul_f32 v[112:113], v[164:165], v[110:111]
	v_cvt_pk_bf16_f32 v114, v114, v115
	s_nop 0
	v_cvt_pk_bf16_f32 v115, v112, v113
	global_store_dwordx2 v[116:117], v[114:115], off
	v_mul_f32_e32 v109, v109, v109
	v_mul_f32_e32 v111, v111, v111
	v_fmac_f32_e32 v109, v108, v108
	v_fmac_f32_e32 v111, v110, v110
	v_add_f32_e32 v108, v109, v111
	s_waitcnt vmcnt(18)
	v_pk_fma_f32 v[104:105], v[104:105], v[92:93], v[200:201]
	v_pk_fma_f32 v[106:107], v[106:107], v[94:95], v[202:203]
	v_pk_mul_f32 v[114:115], v[162:163], v[104:105]
	global_store_dwordx4 v[118:119], v[104:107], off offset:64
	v_pk_mul_f32 v[112:113], v[160:161], v[106:107]
	v_cvt_pk_bf16_f32 v114, v114, v115
	s_nop 0
	v_cvt_pk_bf16_f32 v115, v112, v113
	global_store_dwordx2 v[116:117], v[114:115], off offset:32
	v_mul_f32_e32 v105, v105, v105
	v_mul_f32_e32 v107, v107, v107
	v_fmac_f32_e32 v105, v104, v104
	v_fmac_f32_e32 v107, v106, v106
	v_add_f32_e32 v104, v105, v107
	v_add_f32_e32 v104, v108, v104
	s_waitcnt vmcnt(19)
	v_pk_fma_f32 v[100:101], v[100:101], v[76:77], v[204:205]
	v_pk_fma_f32 v[102:103], v[102:103], v[78:79], v[206:207]
	v_pk_mul_f32 v[114:115], v[158:159], v[100:101]
	global_store_dwordx4 v[118:119], v[100:103], off offset:512
	v_pk_mul_f32 v[112:113], v[156:157], v[102:103]
	v_cvt_pk_bf16_f32 v114, v114, v115
	s_nop 0
	v_cvt_pk_bf16_f32 v115, v112, v113
	global_store_dwordx2 v[116:117], v[114:115], off offset:256
	v_mul_f32_e32 v101, v101, v101
	v_mul_f32_e32 v103, v103, v103
	v_fmac_f32_e32 v101, v100, v100
	v_fmac_f32_e32 v103, v102, v102
	v_add_f32_e32 v100, v101, v103
	v_add_f32_e32 v102, v104, v100
	s_waitcnt vmcnt(20)
	v_pk_fma_f32 v[100:101], v[98:99], v[74:75], v[210:211]
	v_pk_fma_f32 v[98:99], v[96:97], v[72:73], v[208:209]
	v_add_u32_e32 v229, 0x80000, v228
	global_load_dwordx4 v[196:199], v229, s[4:5]
	global_load_dwordx4 v[200:203], v229, s[4:5] offset:64
	global_load_dwordx4 v[204:207], v229, s[4:5] offset:512
	global_load_dwordx4 v[208:211], v229, s[4:5] offset:576
	v_mul_f32_e32 v97, v101, v101
	v_mul_f32_e32 v96, v99, v99
	v_fmac_f32_e32 v96, v98, v98
	v_fmac_f32_e32 v97, v100, v100
	v_add_f32_e32 v96, v96, v97
	v_add_f32_e32 v96, v102, v96
	ds_bpermute_b32 v97, v182, v96
	global_store_dwordx4 v[118:119], v[98:101], off offset:576
	s_waitcnt lgkmcnt(0)
	v_add_f32_e32 v96, v96, v97
	ds_bpermute_b32 v97, v183, v96
	v_pk_mul_f32 v[98:99], v[152:153], v[98:99]
	v_pk_mul_f32 v[100:101], v[154:155], v[100:101]
	v_cvt_pk_bf16_f32 v98, v98, v99
	s_nop 0
	v_cvt_pk_bf16_f32 v99, v100, v101
	global_store_dwordx2 v[116:117], v[98:99], off offset:288
	s_and_saveexec_b64 s[36:37], s[6:7]
	s_mov_b32 s70, 0xbf3a00e3
	s_cbranch_execz .LBB0_542
	s_waitcnt lgkmcnt(0)
	v_add_f32_e32 v96, v96, v97
	ds_write_b32 v184, v96 offset:512
; __device__ __forceinline__ unsigned cvt_pk_bf16(float lo, float hi) { unsigned r; asm volatile("v_cvt_pk_bf16_f32 %0, %1, %2" : "=v"(r) : "v"(lo), "v"(hi)); return r; }
; __device__ __forceinline__ float shx(float v, int o, int lane) { return __int_as_float(__builtin_amdgcn_ds_bpermute((lane ^ o) << 2, __float_as_int(v))); }
;     __device__ __forceinline__ void operator()(const f32x4 (&acc)[2][2][4][2], const Unit& u, int wr, int wc, int fr, int fq) const {
;     ...
;             for (int m = 0; m < 4; ++m) { const int row = row0 + ai * HALF + m * 16; const size_t off = (size_t)row * DM + col0; float ss = 0.f;
; #pragma unroll
;                 for (int bj = 0; bj < 2; ++bj)
; #pragma unroll
;                     for (int n = 0; n < 2; ++n) { const f32x4 x = *(const f32x4*)(src + off + bj * HALF + n * 16) + gv[bj][n] * acc[ai][bj][m][n];
;                         *(f32x4*)(dst + off + bj * HALF + n * 16) = x; ss += (x[0] * x[0] + x[1] * x[1]) + (x[2] * x[2] + x[3] * x[3]);
;                         const f32x4 hh = x * gs[bj][n]; u32x2 w; w.x = cvt_pk_bf16(hh[0], hh[1]); w.y = cvt_pk_bf16(hh[2], hh[3]); *(u32x2*)(Hn + off + bj * HALF + n * 16) = w; }
;                 ss += shx(ss, 16, lane); ss += shx(ss, 32, lane);
;                 if (fq == 0) scr[(ai * HALF + wr * 64 + m * 16 + fr) * 4 + wc] = ss; }
.LBB0_542:
	s_or_b64 exec, exec, s[36:37]
	v_or_b32_e32 v96, 48, v170
	s_waitcnt lgkmcnt(0)
	v_ashrrev_i32_e32 v97, 31, v96
	v_lshlrev_b64 v[96:97], 10, v[96:97]
	v_lshl_add_u64 v[100:101], v[96:97], 0, v[168:169]
	v_lshlrev_b64 v[102:103], 2, v[100:101]
	v_lshl_add_u64 v[104:105], s[4:5], 0, v[102:103]
	v_lshl_add_u64 v[100:101], v[100:101], 1, s[18:19]
	v_lshl_add_u64 v[102:103], s[12:13], 0, v[102:103]
	s_waitcnt vmcnt(17)
	v_pk_fma_f32 v[84:85], v[84:85], v[88:89], v[212:213]
	v_pk_fma_f32 v[86:87], v[86:87], v[90:91], v[214:215]
	v_pk_mul_f32 v[98:99], v[166:167], v[84:85]
	global_store_dwordx4 v[102:103], v[84:87], off
	v_pk_mul_f32 v[96:97], v[164:165], v[86:87]
	v_cvt_pk_bf16_f32 v98, v98, v99
	s_nop 0
	v_cvt_pk_bf16_f32 v99, v96, v97
	global_store_dwordx2 v[100:101], v[98:99], off
	v_mul_f32_e32 v85, v85, v85
	v_mul_f32_e32 v87, v87, v87
	v_fmac_f32_e32 v85, v84, v84
	v_fmac_f32_e32 v87, v86, v86
	v_add_f32_e32 v84, v85, v87
	s_waitcnt vmcnt(18)
	v_pk_fma_f32 v[80:81], v[80:81], v[92:93], v[216:217]
	v_pk_fma_f32 v[82:83], v[82:83], v[94:95], v[218:219]
	v_pk_mul_f32 v[98:99], v[162:163], v[80:81]
	global_store_dwordx4 v[102:103], v[80:83], off offset:64
	v_pk_mul_f32 v[96:97], v[160:161], v[82:83]
	v_cvt_pk_bf16_f32 v98, v98, v99
	s_nop 0
	v_cvt_pk_bf16_f32 v99, v96, v97
	global_store_dwordx2 v[100:101], v[98:99], off offset:32
	v_mul_f32_e32 v81, v81, v81
	v_mul_f32_e32 v83, v83, v83
	v_fmac_f32_e32 v81, v80, v80
	v_fmac_f32_e32 v83, v82, v82
	v_add_f32_e32 v80, v81, v83
	v_add_f32_e32 v80, v84, v80
	s_waitcnt vmcnt(19)
	v_pk_fma_f32 v[68:69], v[68:69], v[76:77], v[220:221]
	v_pk_fma_f32 v[70:71], v[70:71], v[78:79], v[222:223]
	v_pk_mul_f32 v[98:99], v[158:159], v[68:69]
	global_store_dwordx4 v[102:103], v[68:71], off offset:512
	v_pk_mul_f32 v[96:97], v[156:157], v[70:71]
	v_cvt_pk_bf16_f32 v98, v98, v99
	s_nop 0
	v_cvt_pk_bf16_f32 v99, v96, v97
	global_store_dwordx2 v[100:101], v[98:99], off offset:256
	v_mul_f32_e32 v69, v69, v69
	v_mul_f32_e32 v71, v71, v71
	v_fmac_f32_e32 v69, v68, v68
	v_fmac_f32_e32 v71, v70, v70
	v_add_f32_e32 v68, v69, v71
	v_add_f32_e32 v70, v80, v68
	s_waitcnt vmcnt(20)
	v_pk_fma_f32 v[68:69], v[66:67], v[74:75], v[226:227]
	v_pk_fma_f32 v[66:67], v[64:65], v[72:73], v[224:225]
	v_add_u32_e32 v229, 0x90000, v228
	global_load_dwordx4 v[212:215], v229, s[4:5]
	global_load_dwordx4 v[216:219], v229, s[4:5] offset:64
	global_load_dwordx4 v[220:223], v229, s[4:5] offset:512
	global_load_dwordx4 v[224:227], v229, s[4:5] offset:576
	v_mul_f32_e32 v65, v69, v69
	v_mul_f32_e32 v64, v67, v67
	v_fmac_f32_e32 v64, v66, v66
	v_fmac_f32_e32 v65, v68, v68
	v_add_f32_e32 v64, v64, v65
	v_add_f32_e32 v64, v70, v64
	ds_bpermute_b32 v65, v182, v64
	global_store_dwordx4 v[102:103], v[66:69], off offset:576
	s_waitcnt lgkmcnt(0)
	v_add_f32_e32 v64, v64, v65
	ds_bpermute_b32 v65, v183, v64
	v_pk_mul_f32 v[66:67], v[152:153], v[66:67]
	v_pk_mul_f32 v[68:69], v[154:155], v[68:69]
	v_cvt_pk_bf16_f32 v66, v66, v67
	s_nop 0
	v_cvt_pk_bf16_f32 v67, v68, v69
	global_store_dwordx2 v[100:101], v[66:67], off offset:288
	s_and_saveexec_b64 s[36:37], s[6:7]
	s_cbranch_execz .LBB0_544
	s_waitcnt lgkmcnt(0)
	v_add_f32_e32 v64, v64, v65
	ds_write_b32 v184, v64 offset:768
.LBB0_544:
	s_or_b64 exec, exec, s[36:37]
	s_waitcnt lgkmcnt(0)
	v_lshlrev_b64 v[64:65], 10, v[170:171]
	v_lshl_add_u64 v[64:65], v[64:65], 0, v[168:169]
	s_mov_b64 s[36:37], 0x20000
	v_lshl_add_u64 v[70:71], v[64:65], 0, s[36:37]
	v_lshlrev_b64 v[80:81], 2, v[70:71]
	v_lshl_add_u64 v[82:83], s[4:5], 0, v[80:81]
	v_lshl_add_u64 v[70:71], v[70:71], 1, s[18:19]
	v_lshl_add_u64 v[80:81], s[12:13], 0, v[80:81]
	s_waitcnt vmcnt(17)
	v_pk_fma_f32 v[60:61], v[60:61], v[88:89], v[196:197]
	v_pk_fma_f32 v[62:63], v[62:63], v[90:91], v[198:199]
	v_pk_mul_f32 v[68:69], v[166:167], v[60:61]
	global_store_dwordx4 v[80:81], v[60:63], off
	v_pk_mul_f32 v[66:67], v[164:165], v[62:63]
	v_cvt_pk_bf16_f32 v68, v68, v69
	s_nop 0
	v_cvt_pk_bf16_f32 v69, v66, v67
	global_store_dwordx2 v[70:71], v[68:69], off
	v_mul_f32_e32 v61, v61, v61
	v_mul_f32_e32 v63, v63, v63
	v_fmac_f32_e32 v61, v60, v60
	v_fmac_f32_e32 v63, v62, v62
	v_add_f32_e32 v60, v61, v63
	s_waitcnt vmcnt(18)
	v_pk_fma_f32 v[56:57], v[56:57], v[92:93], v[200:201]
	v_pk_fma_f32 v[58:59], v[58:59], v[94:95], v[202:203]
	v_pk_mul_f32 v[68:69], v[162:163], v[56:57]
	global_store_dwordx4 v[80:81], v[56:59], off offset:64
	v_pk_mul_f32 v[66:67], v[160:161], v[58:59]
	v_cvt_pk_bf16_f32 v68, v68, v69
	s_nop 0
	v_cvt_pk_bf16_f32 v69, v66, v67
	global_store_dwordx2 v[70:71], v[68:69], off offset:32
	v_mul_f32_e32 v57, v57, v57
	v_mul_f32_e32 v59, v59, v59
	v_fmac_f32_e32 v57, v56, v56
	v_fmac_f32_e32 v59, v58, v58
	v_add_f32_e32 v56, v57, v59
	v_add_f32_e32 v56, v60, v56
	s_waitcnt vmcnt(19)
	v_pk_fma_f32 v[52:53], v[52:53], v[76:77], v[204:205]
	v_pk_fma_f32 v[54:55], v[54:55], v[78:79], v[206:207]
	v_pk_mul_f32 v[68:69], v[158:159], v[52:53]
	global_store_dwordx4 v[80:81], v[52:55], off offset:512
	v_pk_mul_f32 v[66:67], v[156:157], v[54:55]
	v_cvt_pk_bf16_f32 v68, v68, v69
	s_nop 0
	v_cvt_pk_bf16_f32 v69, v66, v67
	global_store_dwordx2 v[70:71], v[68:69], off offset:256
	v_mul_f32_e32 v53, v53, v53
	v_mul_f32_e32 v55, v55, v55
	v_fmac_f32_e32 v53, v52, v52
	v_fmac_f32_e32 v55, v54, v54
	v_add_f32_e32 v52, v53, v55
	v_add_f32_e32 v54, v56, v52
	s_waitcnt vmcnt(20)
	v_pk_fma_f32 v[52:53], v[50:51], v[74:75], v[210:211]
	v_pk_fma_f32 v[50:51], v[48:49], v[72:73], v[208:209]
	v_add_u32_e32 v229, 0xa0000, v228
	global_load_dwordx4 v[196:199], v229, s[4:5]
	global_load_dwordx4 v[200:203], v229, s[4:5] offset:64
	global_load_dwordx4 v[204:207], v229, s[4:5] offset:512
	global_load_dwordx4 v[208:211], v229, s[4:5] offset:576
	v_mul_f32_e32 v49, v53, v53
	v_mul_f32_e32 v48, v51, v51
	v_fmac_f32_e32 v48, v50, v50
	v_fmac_f32_e32 v49, v52, v52
	v_add_f32_e32 v48, v48, v49
	v_add_f32_e32 v48, v54, v48
	ds_bpermute_b32 v49, v182, v48
	global_store_dwordx4 v[80:81], v[50:53], off offset:576
	s_waitcnt lgkmcnt(0)
	v_add_f32_e32 v48, v48, v49
	ds_bpermute_b32 v49, v183, v48
	v_pk_mul_f32 v[50:51], v[152:153], v[50:51]
	v_pk_mul_f32 v[52:53], v[154:155], v[52:53]
	v_cvt_pk_bf16_f32 v50, v50, v51
	s_nop 0
	v_cvt_pk_bf16_f32 v51, v52, v53
	global_store_dwordx2 v[70:71], v[50:51], off offset:288
	s_and_saveexec_b64 s[36:37], s[6:7]
	s_cbranch_execz .LBB0_546
	s_waitcnt lgkmcnt(0)
	v_add_f32_e32 v48, v48, v49
	ds_write_b32 v184, v48 offset:2048
; __device__ __forceinline__ unsigned cvt_pk_bf16(float lo, float hi) { unsigned r; asm volatile("v_cvt_pk_bf16_f32 %0, %1, %2" : "=v"(r) : "v"(lo), "v"(hi)); return r; }
; __device__ __forceinline__ float shx(float v, int o, int lane) { return __int_as_float(__builtin_amdgcn_ds_bpermute((lane ^ o) << 2, __float_as_int(v))); }
;     __device__ __forceinline__ void operator()(const f32x4 (&acc)[2][2][4][2], const Unit& u, int wr, int wc, int fr, int fq) const {
;     ...
;             for (int m = 0; m < 4; ++m) { const int row = row0 + ai * HALF + m * 16; const size_t off = (size_t)row * DM + col0; float ss = 0.f;
; #pragma unroll
;                 for (int bj = 0; bj < 2; ++bj)
; #pragma unroll
;                     for (int n = 0; n < 2; ++n) { const f32x4 x = *(const f32x4*)(src + off + bj * HALF + n * 16) + gv[bj][n] * acc[ai][bj][m][n];
;                         *(f32x4*)(dst + off + bj * HALF + n * 16) = x; ss += (x[0] * x[0] + x[1] * x[1]) + (x[2] * x[2] + x[3] * x[3]);
;                         const f32x4 hh = x * gs[bj][n]; u32x2 w; w.x = cvt_pk_bf16(hh[0], hh[1]); w.y = cvt_pk_bf16(hh[2], hh[3]); *(u32x2*)(Hn + off + bj * HALF + n * 16) = w; }
;                 ss += shx(ss, 16, lane); ss += shx(ss, 32, lane);
;                 if (fq == 0) scr[(ai * HALF + wr * 64 + m * 16 + fr) * 4 + wc] = ss; }
.LBB0_546:
	s_or_b64 exec, exec, s[36:37]
	s_mov_b64 s[36:37], 0x24000
	v_lshl_add_u64 v[52:53], v[64:65], 0, s[36:37]
	v_lshlrev_b64 v[54:55], 2, v[52:53]
	v_lshl_add_u64 v[56:57], s[4:5], 0, v[54:55]
	s_waitcnt lgkmcnt(0)
	v_lshl_add_u64 v[52:53], v[52:53], 1, s[18:19]
	v_lshl_add_u64 v[54:55], s[12:13], 0, v[54:55]
	s_waitcnt vmcnt(17)
	v_pk_fma_f32 v[44:45], v[44:45], v[88:89], v[212:213]
	v_pk_fma_f32 v[46:47], v[46:47], v[90:91], v[214:215]
	v_pk_mul_f32 v[50:51], v[166:167], v[44:45]
	global_store_dwordx4 v[54:55], v[44:47], off
	v_pk_mul_f32 v[48:49], v[164:165], v[46:47]
	v_cvt_pk_bf16_f32 v50, v50, v51
	s_nop 0
	v_cvt_pk_bf16_f32 v51, v48, v49
	global_store_dwordx2 v[52:53], v[50:51], off
	v_mul_f32_e32 v45, v45, v45
	v_mul_f32_e32 v47, v47, v47
	v_fmac_f32_e32 v45, v44, v44
	v_fmac_f32_e32 v47, v46, v46
	v_add_f32_e32 v44, v45, v47
	s_waitcnt vmcnt(18)
	v_pk_fma_f32 v[40:41], v[40:41], v[92:93], v[216:217]
	v_pk_fma_f32 v[42:43], v[42:43], v[94:95], v[218:219]
	v_pk_mul_f32 v[50:51], v[162:163], v[40:41]
	global_store_dwordx4 v[54:55], v[40:43], off offset:64
	v_pk_mul_f32 v[48:49], v[160:161], v[42:43]
	v_cvt_pk_bf16_f32 v50, v50, v51
	s_nop 0
	v_cvt_pk_bf16_f32 v51, v48, v49
	global_store_dwordx2 v[52:53], v[50:51], off offset:32
	v_mul_f32_e32 v41, v41, v41
	v_mul_f32_e32 v43, v43, v43
	v_fmac_f32_e32 v41, v40, v40
	v_fmac_f32_e32 v43, v42, v42
	v_add_f32_e32 v40, v41, v43
	v_add_f32_e32 v40, v44, v40
	s_waitcnt vmcnt(19)
	v_pk_fma_f32 v[36:37], v[36:37], v[76:77], v[220:221]
	v_pk_fma_f32 v[38:39], v[38:39], v[78:79], v[222:223]
	v_pk_mul_f32 v[50:51], v[158:159], v[36:37]
	global_store_dwordx4 v[54:55], v[36:39], off offset:512
	v_pk_mul_f32 v[48:49], v[156:157], v[38:39]
	v_cvt_pk_bf16_f32 v50, v50, v51
	s_nop 0
	v_cvt_pk_bf16_f32 v51, v48, v49
	global_store_dwordx2 v[52:53], v[50:51], off offset:256
	v_mul_f32_e32 v37, v37, v37
	v_mul_f32_e32 v39, v39, v39
	v_fmac_f32_e32 v37, v36, v36
	v_fmac_f32_e32 v39, v38, v38
	v_add_f32_e32 v36, v37, v39
	v_add_f32_e32 v38, v40, v36
	s_waitcnt vmcnt(20)
	v_pk_fma_f32 v[36:37], v[34:35], v[74:75], v[226:227]
	v_pk_fma_f32 v[34:35], v[32:33], v[72:73], v[224:225]
	v_add_u32_e32 v229, 0xb0000, v228
	global_load_dwordx4 v[212:215], v229, s[4:5]
	global_load_dwordx4 v[216:219], v229, s[4:5] offset:64
	global_load_dwordx4 v[220:223], v229, s[4:5] offset:512
	global_load_dwordx4 v[224:227], v229, s[4:5] offset:576
	v_mul_f32_e32 v33, v37, v37
	v_mul_f32_e32 v32, v35, v35
	v_fmac_f32_e32 v32, v34, v34
	v_fmac_f32_e32 v33, v36, v36
	v_add_f32_e32 v32, v32, v33
	v_add_f32_e32 v32, v38, v32
	ds_bpermute_b32 v33, v182, v32
	global_store_dwordx4 v[54:55], v[34:37], off offset:576
	s_waitcnt lgkmcnt(0)
	v_add_f32_e32 v32, v32, v33
	ds_bpermute_b32 v33, v183, v32
	v_pk_mul_f32 v[34:35], v[152:153], v[34:35]
	v_pk_mul_f32 v[36:37], v[154:155], v[36:37]
	v_cvt_pk_bf16_f32 v34, v34, v35
	s_nop 0
	v_cvt_pk_bf16_f32 v35, v36, v37
	global_store_dwordx2 v[52:53], v[34:35], off offset:288
	s_and_saveexec_b64 s[36:37], s[6:7]
	s_cbranch_execz .LBB0_548
	s_waitcnt lgkmcnt(0)
	v_add_f32_e32 v32, v32, v33
	ds_write_b32 v184, v32 offset:2304
; __device__ __forceinline__ unsigned cvt_pk_bf16(float lo, float hi) { unsigned r; asm volatile("v_cvt_pk_bf16_f32 %0, %1, %2" : "=v"(r) : "v"(lo), "v"(hi)); return r; }
; __device__ __forceinline__ float shx(float v, int o, int lane) { return __int_as_float(__builtin_amdgcn_ds_bpermute((lane ^ o) << 2, __float_as_int(v))); }
;     __device__ __forceinline__ void operator()(const f32x4 (&acc)[2][2][4][2], const Unit& u, int wr, int wc, int fr, int fq) const {
;     ...
;             for (int m = 0; m < 4; ++m) { const int row = row0 + ai * HALF + m * 16; const size_t off = (size_t)row * DM + col0; float ss = 0.f;
; #pragma unroll
;                 for (int bj = 0; bj < 2; ++bj)
; #pragma unroll
;                     for (int n = 0; n < 2; ++n) { const f32x4 x = *(const f32x4*)(src + off + bj * HALF + n * 16) + gv[bj][n] * acc[ai][bj][m][n];
;                         *(f32x4*)(dst + off + bj * HALF + n * 16) = x; ss += (x[0] * x[0] + x[1] * x[1]) + (x[2] * x[2] + x[3] * x[3]);
;                         const f32x4 hh = x * gs[bj][n]; u32x2 w; w.x = cvt_pk_bf16(hh[0], hh[1]); w.y = cvt_pk_bf16(hh[2], hh[3]); *(u32x2*)(Hn + off + bj * HALF + n * 16) = w; }
;                 ss += shx(ss, 16, lane); ss += shx(ss, 32, lane);
;                 if (fq == 0) scr[(ai * HALF + wr * 64 + m * 16 + fr) * 4 + wc] = ss; }
.LBB0_548:
	s_or_b64 exec, exec, s[36:37]
	s_waitcnt lgkmcnt(0)
	v_lshlrev_b64 v[32:33], 10, v[170:171]
	v_lshl_add_u64 v[32:33], v[32:33], 0, v[168:169]
	s_mov_b64 s[36:37], 0x28000
	v_lshl_add_u64 v[38:39], v[32:33], 0, s[36:37]
	v_lshlrev_b64 v[40:41], 2, v[38:39]
	v_lshl_add_u64 v[42:43], s[4:5], 0, v[40:41]
	v_lshl_add_u64 v[38:39], v[38:39], 1, s[18:19]
	v_lshl_add_u64 v[40:41], s[12:13], 0, v[40:41]
	s_waitcnt vmcnt(17)
	v_pk_fma_f32 v[28:29], v[28:29], v[88:89], v[196:197]
	v_pk_fma_f32 v[30:31], v[30:31], v[90:91], v[198:199]
	v_pk_mul_f32 v[36:37], v[166:167], v[28:29]
	global_store_dwordx4 v[40:41], v[28:31], off
	v_pk_mul_f32 v[34:35], v[164:165], v[30:31]
	v_cvt_pk_bf16_f32 v36, v36, v37
	s_nop 0
	v_cvt_pk_bf16_f32 v37, v34, v35
	global_store_dwordx2 v[38:39], v[36:37], off
	v_mul_f32_e32 v29, v29, v29
	v_mul_f32_e32 v31, v31, v31
	v_fmac_f32_e32 v29, v28, v28
	v_fmac_f32_e32 v31, v30, v30
	v_add_f32_e32 v28, v29, v31
	s_waitcnt vmcnt(18)
	v_pk_fma_f32 v[24:25], v[24:25], v[92:93], v[200:201]
	v_pk_fma_f32 v[26:27], v[26:27], v[94:95], v[202:203]
	v_pk_mul_f32 v[36:37], v[162:163], v[24:25]
	global_store_dwordx4 v[40:41], v[24:27], off offset:64
	v_pk_mul_f32 v[34:35], v[160:161], v[26:27]
	v_cvt_pk_bf16_f32 v36, v36, v37
	s_nop 0
	v_cvt_pk_bf16_f32 v37, v34, v35
	global_store_dwordx2 v[38:39], v[36:37], off offset:32
	v_mul_f32_e32 v25, v25, v25
	v_mul_f32_e32 v27, v27, v27
	v_fmac_f32_e32 v25, v24, v24
	v_fmac_f32_e32 v27, v26, v26
	v_add_f32_e32 v24, v25, v27
	v_add_f32_e32 v24, v28, v24
	s_waitcnt vmcnt(19)
	v_pk_fma_f32 v[20:21], v[20:21], v[76:77], v[204:205]
	v_pk_fma_f32 v[22:23], v[22:23], v[78:79], v[206:207]
	v_pk_mul_f32 v[36:37], v[158:159], v[20:21]
	global_store_dwordx4 v[40:41], v[20:23], off offset:512
	v_pk_mul_f32 v[34:35], v[156:157], v[22:23]
	v_cvt_pk_bf16_f32 v36, v36, v37
	s_nop 0
	v_cvt_pk_bf16_f32 v37, v34, v35
	global_store_dwordx2 v[38:39], v[36:37], off offset:256
	v_mul_f32_e32 v21, v21, v21
	v_mul_f32_e32 v23, v23, v23
	v_fmac_f32_e32 v21, v20, v20
	v_fmac_f32_e32 v23, v22, v22
	v_add_f32_e32 v20, v21, v23
	v_add_f32_e32 v22, v24, v20
	s_waitcnt vmcnt(20)
	v_pk_fma_f32 v[20:21], v[18:19], v[74:75], v[210:211]
	v_pk_fma_f32 v[18:19], v[16:17], v[72:73], v[208:209]
	v_mul_f32_e32 v17, v21, v21
	v_mul_f32_e32 v16, v19, v19
	v_fmac_f32_e32 v16, v18, v18
	v_fmac_f32_e32 v17, v20, v20
	v_add_f32_e32 v16, v16, v17
	v_add_f32_e32 v16, v22, v16
	ds_bpermute_b32 v17, v182, v16
	global_store_dwordx4 v[40:41], v[18:21], off offset:576
	s_waitcnt lgkmcnt(0)
	v_add_f32_e32 v16, v16, v17
	ds_bpermute_b32 v17, v183, v16
	v_pk_mul_f32 v[18:19], v[152:153], v[18:19]
	v_pk_mul_f32 v[20:21], v[154:155], v[20:21]
	v_cvt_pk_bf16_f32 v18, v18, v19
	s_nop 0
	v_cvt_pk_bf16_f32 v19, v20, v21
	global_store_dwordx2 v[38:39], v[18:19], off offset:288
	s_and_saveexec_b64 s[36:37], s[6:7]
	s_cbranch_execz .LBB0_550
	s_waitcnt lgkmcnt(0)
	v_add_f32_e32 v16, v16, v17
	ds_write_b32 v184, v16 offset:2560
.LBB0_550:
	s_or_b64 exec, exec, s[36:37]
	s_mov_b64 s[36:37], 0x2c000
	v_lshl_add_u64 v[20:21], v[32:33], 0, s[36:37]
	v_lshlrev_b64 v[22:23], 2, v[20:21]
	v_lshl_add_u64 v[24:25], s[4:5], 0, v[22:23]
	s_waitcnt lgkmcnt(0)
	v_lshl_add_u64 v[20:21], v[20:21], 1, s[18:19]
	v_lshl_add_u64 v[22:23], s[12:13], 0, v[22:23]
	s_waitcnt vmcnt(13)
	v_pk_fma_f32 v[12:13], v[12:13], v[88:89], v[212:213]
	v_pk_fma_f32 v[14:15], v[14:15], v[90:91], v[214:215]
	v_pk_mul_f32 v[18:19], v[166:167], v[12:13]
	global_store_dwordx4 v[22:23], v[12:15], off
	v_pk_mul_f32 v[16:17], v[164:165], v[14:15]
	v_cvt_pk_bf16_f32 v18, v18, v19
	s_nop 0
	v_cvt_pk_bf16_f32 v19, v16, v17
	global_store_dwordx2 v[20:21], v[18:19], off
	v_mul_f32_e32 v13, v13, v13
	v_mul_f32_e32 v15, v15, v15
	v_fmac_f32_e32 v13, v12, v12
	v_fmac_f32_e32 v15, v14, v14
	v_add_f32_e32 v12, v13, v15
	s_waitcnt vmcnt(14)
	v_pk_fma_f32 v[8:9], v[8:9], v[92:93], v[216:217]
	v_pk_fma_f32 v[10:11], v[10:11], v[94:95], v[218:219]
	v_pk_mul_f32 v[18:19], v[162:163], v[8:9]
	global_store_dwordx4 v[22:23], v[8:11], off offset:64
	v_pk_mul_f32 v[16:17], v[160:161], v[10:11]
	v_cvt_pk_bf16_f32 v18, v18, v19
	s_nop 0
	v_cvt_pk_bf16_f32 v19, v16, v17
	global_store_dwordx2 v[20:21], v[18:19], off offset:32
	v_mul_f32_e32 v9, v9, v9
	v_mul_f32_e32 v11, v11, v11
	v_fmac_f32_e32 v9, v8, v8
	v_fmac_f32_e32 v11, v10, v10
	v_add_f32_e32 v8, v9, v11
	v_add_f32_e32 v8, v12, v8
	s_waitcnt vmcnt(15)
	v_pk_fma_f32 v[4:5], v[4:5], v[76:77], v[220:221]
	v_pk_fma_f32 v[6:7], v[6:7], v[78:79], v[222:223]
	v_pk_mul_f32 v[18:19], v[158:159], v[4:5]
	global_store_dwordx4 v[22:23], v[4:7], off offset:512
	v_pk_mul_f32 v[16:17], v[156:157], v[6:7]
	v_cvt_pk_bf16_f32 v18, v18, v19
	s_nop 0
	v_cvt_pk_bf16_f32 v19, v16, v17
	global_store_dwordx2 v[20:21], v[18:19], off offset:256
	v_mul_f32_e32 v5, v5, v5
	v_mul_f32_e32 v7, v7, v7
	v_fmac_f32_e32 v5, v4, v4
	v_fmac_f32_e32 v7, v6, v6
	v_add_f32_e32 v4, v5, v7
	v_add_f32_e32 v6, v8, v4
	s_waitcnt vmcnt(16)
	v_pk_fma_f32 v[4:5], v[2:3], v[74:75], v[226:227]
	v_pk_fma_f32 v[2:3], v[0:1], v[72:73], v[224:225]
	v_mul_f32_e32 v1, v5, v5
	v_mul_f32_e32 v0, v3, v3
	v_fmac_f32_e32 v0, v2, v2
	v_fmac_f32_e32 v1, v4, v4
	v_add_f32_e32 v0, v0, v1
	v_add_f32_e32 v0, v6, v0
	ds_bpermute_b32 v1, v182, v0
	global_store_dwordx4 v[22:23], v[2:5], off offset:576
	s_waitcnt lgkmcnt(0)
	v_add_f32_e32 v0, v0, v1
	ds_bpermute_b32 v1, v183, v0
	v_pk_mul_f32 v[2:3], v[152:153], v[2:3]
	v_pk_mul_f32 v[4:5], v[154:155], v[4:5]
	v_cvt_pk_bf16_f32 v2, v2, v3
	s_nop 0
	v_cvt_pk_bf16_f32 v3, v4, v5
	global_store_dwordx2 v[20:21], v[2:3], off offset:288
	s_and_saveexec_b64 s[36:37], s[6:7]
	s_cbranch_execz .LBB0_552
	s_waitcnt lgkmcnt(0)
	v_add_f32_e32 v0, v0, v1
	ds_write_b32 v184, v0 offset:2816

; __device__ __forceinline__ unsigned cvt_pk_bf16(float lo, float hi) { unsigned r; asm volatile("v_cvt_pk_bf16_f32 %0, %1, %2" : "=v"(r) : "v"(lo), "v"(hi)); return r; }
; __device__ __forceinline__ float shx(float v, int o, int lane) { return __int_as_float(__builtin_amdgcn_ds_bpermute((lane ^ o) << 2, __float_as_int(v))); }
;     __device__ __forceinline__ void operator()(const f32x4 (&acc)[2][2][4][2], const Unit& u, int wr, int wc, int fr, int fq) const {
;         const int bidx = u.pm >> 4, row0 = u.pm * BM + wr * 64 + fr, col0 = u.pn * BM + wc * 32 + 4 * fq, lane = fq * 16 + fr;
;         f32x4 gv[2][2], gs[2][2];
; #pragma unroll
;         for (int bj = 0; bj < 2; ++bj)
; #pragma unroll
;             for (int n = 0; n < 2; ++n) { const int c = col0 + bj * HALF + n * 16; gv[bj][n] = *(const f32x4*)(gate + (size_t)bidx * NMOD + c);
;                 gs[bj][n] = *(const f32x4*)(gnext + c) * (*(const f32x4*)(scn + (size_t)bidx * NMOD + c) + 1.0f); }
; #pragma unroll
;         for (int ai = 0; ai < 2; ++ai)
; #pragma unroll
;             for (int m = 0; m < 4; ++m) { const int row = row0 + ai * HALF + m * 16; const size_t off = (size_t)row * DM + col0; float ss = 0.f;
; #pragma unroll
;                 for (int bj = 0; bj < 2; ++bj)
; #pragma unroll
;                     for (int n = 0; n < 2; ++n) { const f32x4 x = *(const f32x4*)(src + off + bj * HALF + n * 16) + gv[bj][n] * acc[ai][bj][m][n];
;                         *(f32x4*)(dst + off + bj * HALF + n * 16) = x; ss += (x[0] * x[0] + x[1] * x[1]) + (x[2] * x[2] + x[3] * x[3]);
;                         const f32x4 hh = x * gs[bj][n]; u32x2 w; w.x = cvt_pk_bf16(hh[0], hh[1]); w.y = cvt_pk_bf16(hh[2], hh[3]); *(u32x2*)(Hn + off + bj * HALF + n * 16) = w; }
;                 ss += shx(ss, 16, lane); ss += shx(ss, 32, lane);
;                 if (fq == 0) scr[(ai * HALF + wr * 64 + m * 16 + fr) * 4 + wc] = ss; }
.LBB0_1578:
	s_ashr_i32 s25, s34, 4
	s_lshl_b32 s34, s34, 8
	s_mul_hi_i32 s27, s25, 0x6000
	s_mulk_i32 s25, 0x6000
	v_lshl_or_b32 v168, s36, 8, v185
	s_add_u32 s36, s55, s25
	s_addc_u32 s37, s56, s27
	s_add_u32 s38, s57, s25
	v_ashrrev_i32_e32 v169, 31, v168
	s_addc_u32 s39, s58, s27
	v_lshlrev_b64 v[76:77], 2, v[168:169]
	v_lshl_add_u64 v[176:177], s[38:39], 0, v[76:77]
	v_lshl_add_u64 v[170:171], s[36:37], 0, v[76:77]
	v_lshl_add_u64 v[174:175], s[20:21], 0, v[76:77]
	global_load_dwordx4 v[76:79], v[176:177], off
	global_load_dwordx4 v[72:75], v[174:175], off
	global_load_dwordx4 v[88:91], v[170:171], off
	s_waitcnt vmcnt(0)
	v_pk_add_f32 v[78:79], v[78:79], 1.0 op_sel_hi:[1,0]
	v_pk_add_f32 v[76:77], v[76:77], 1.0 op_sel_hi:[1,0]
	v_pk_mul_f32 v[164:165], v[74:75], v[78:79]
	v_pk_mul_f32 v[166:167], v[72:73], v[76:77]
	global_load_dwordx4 v[92:95], v[170:171], off offset:64
	global_load_dwordx4 v[72:75], v[174:175], off offset:64
	global_load_dwordx4 v[76:79], v[176:177], off offset:64
	s_waitcnt vmcnt(0)
	v_pk_add_f32 v[78:79], v[78:79], 1.0 op_sel_hi:[1,0]
	v_pk_add_f32 v[76:77], v[76:77], 1.0 op_sel_hi:[1,0]
	v_pk_mul_f32 v[160:161], v[74:75], v[78:79]
	v_pk_mul_f32 v[162:163], v[72:73], v[76:77]
	global_load_dwordx4 v[76:79], v[170:171], off offset:512
	global_load_dwordx4 v[72:75], v[174:175], off offset:512
	global_load_dwordx4 v[152:155], v[176:177], off offset:512
	s_waitcnt vmcnt(0)
	v_pk_add_f32 v[154:155], v[154:155], 1.0 op_sel_hi:[1,0]
	v_pk_add_f32 v[152:153], v[152:153], 1.0 op_sel_hi:[1,0]
	v_pk_mul_f32 v[156:157], v[74:75], v[154:155]
	v_pk_mul_f32 v[158:159], v[72:73], v[152:153]
	global_load_dwordx4 v[72:75], v[170:171], off offset:576
	global_load_dwordx4 v[152:155], v[174:175], off offset:576
	s_nop 0
	global_load_dwordx4 v[174:177], v[176:177], off offset:576
	s_waitcnt vmcnt(0)
	v_pk_add_f32 v[170:171], v[176:177], 1.0 op_sel_hi:[1,0]
	s_nop 0
	v_pk_mul_f32 v[154:155], v[154:155], v[170:171]
	v_add_u32_e32 v170, s34, v180
	v_pk_add_f32 v[174:175], v[174:175], 1.0 op_sel_hi:[1,0]
	v_ashrrev_i32_e32 v171, 31, v170
	v_pk_mul_f32 v[152:153], v[152:153], v[174:175]
	v_lshlrev_b64 v[174:175], 10, v[170:171]
	v_lshl_add_u64 v[192:193], v[174:175], 0, v[168:169]
	v_lshlrev_b64 v[194:195], 2, v[192:193]
	v_lshl_add_u64 v[178:179], s[4:5], 0, v[194:195]
	v_mov_b32_e32 v228, v194
	v_mov_b32_e32 v229, v228
	global_load_dwordx4 v[196:199], v229, s[4:5]
	global_load_dwordx4 v[200:203], v229, s[4:5] offset:64
	global_load_dwordx4 v[204:207], v229, s[4:5] offset:512
	global_load_dwordx4 v[208:211], v229, s[4:5] offset:576
	v_add_u32_e32 v229, 0x10000, v228
	global_load_dwordx4 v[212:215], v229, s[4:5]
	global_load_dwordx4 v[216:219], v229, s[4:5] offset:64
	global_load_dwordx4 v[220:223], v229, s[4:5] offset:512
	global_load_dwordx4 v[224:227], v229, s[4:5] offset:576
	s_waitcnt vmcnt(7)
	v_pk_fma_f32 v[176:177], v[142:143], v[90:91], v[198:199]
	v_pk_fma_f32 v[174:175], v[140:141], v[88:89], v[196:197]
	v_mul_f32_e32 v143, v177, v177
	v_mul_f32_e32 v142, v175, v175
	v_lshl_add_u64 v[140:141], s[12:13], 0, v[194:195]
	v_fmac_f32_e32 v142, v174, v174
	v_fmac_f32_e32 v143, v176, v176
	global_store_dwordx4 v[140:141], v[174:177], off
	v_add_f32_e32 v194, v142, v143
	v_pk_mul_f32 v[142:143], v[164:165], v[176:177]
	v_pk_mul_f32 v[174:175], v[166:167], v[174:175]
	s_nop 0
	v_cvt_pk_bf16_f32 v174, v174, v175
	v_cvt_pk_bf16_f32 v175, v142, v143
	v_lshl_add_u64 v[142:143], v[192:193], 1, s[18:19]
	global_store_dwordx2 v[142:143], v[174:175], off
	s_waitcnt vmcnt(8)
	v_pk_fma_f32 v[136:137], v[136:137], v[92:93], v[200:201]
	v_pk_fma_f32 v[138:139], v[138:139], v[94:95], v[202:203]
	v_mul_f32_e32 v174, v137, v137
	global_store_dwordx4 v[140:141], v[136:139], off offset:64
	v_fmac_f32_e32 v174, v136, v136
	v_mul_f32_e32 v175, v139, v139
	v_pk_mul_f32 v[136:137], v[162:163], v[136:137]
	v_fmac_f32_e32 v175, v138, v138
	v_pk_mul_f32 v[138:139], v[160:161], v[138:139]
	v_cvt_pk_bf16_f32 v136, v136, v137
	v_add_f32_e32 v174, v174, v175
	v_cvt_pk_bf16_f32 v137, v138, v139
	global_store_dwordx2 v[142:143], v[136:137], off offset:32
	v_add_f32_e32 v174, v194, v174
	s_waitcnt vmcnt(9)
	v_pk_fma_f32 v[132:133], v[132:133], v[76:77], v[204:205]
	v_pk_fma_f32 v[134:135], v[134:135], v[78:79], v[206:207]
	v_mul_f32_e32 v136, v133, v133
	global_store_dwordx4 v[140:141], v[132:135], off offset:512
	v_fmac_f32_e32 v136, v132, v132
	v_mul_f32_e32 v137, v135, v135
	v_pk_mul_f32 v[132:133], v[158:159], v[132:133]
	v_fmac_f32_e32 v137, v134, v134
	v_pk_mul_f32 v[134:135], v[156:157], v[134:135]
	v_cvt_pk_bf16_f32 v132, v132, v133
	v_add_f32_e32 v136, v136, v137
	v_cvt_pk_bf16_f32 v133, v134, v135
	global_store_dwordx2 v[142:143], v[132:133], off offset:256
	v_add_f32_e32 v136, v174, v136
	s_waitcnt vmcnt(10)
	v_pk_fma_f32 v[130:131], v[130:131], v[74:75], v[210:211]
	v_pk_fma_f32 v[128:129], v[128:129], v[72:73], v[208:209]
	v_add_u32_e32 v229, 0x20000, v228
	global_load_dwordx4 v[196:199], v229, s[4:5]
	global_load_dwordx4 v[200:203], v229, s[4:5] offset:64
	global_load_dwordx4 v[204:207], v229, s[4:5] offset:512
	global_load_dwordx4 v[208:211], v229, s[4:5] offset:576
	v_mul_f32_e32 v133, v131, v131
	v_mul_f32_e32 v132, v129, v129
	v_fmac_f32_e32 v132, v128, v128
	v_fmac_f32_e32 v133, v130, v130
	global_store_dwordx4 v[140:141], v[128:131], off offset:576
	v_add_f32_e32 v132, v132, v133
	v_add_f32_e32 v132, v136, v132
	v_pk_mul_f32 v[128:129], v[152:153], v[128:129]
	v_pk_mul_f32 v[130:131], v[154:155], v[130:131]
	v_cvt_pk_bf16_f32 v128, v128, v129
	s_nop 0
	v_cvt_pk_bf16_f32 v129, v130, v131
	global_store_dwordx2 v[142:143], v[128:129], off offset:288
	ds_bpermute_b32 v128, v182, v132
	s_waitcnt lgkmcnt(0)
	v_add_f32_e32 v128, v132, v128
	ds_bpermute_b32 v129, v183, v128
	s_and_saveexec_b64 s[36:37], s[6:7]
	s_cbranch_execz .LBB0_1580
	s_waitcnt lgkmcnt(0)
	v_add_f32_e32 v128, v128, v129
	ds_write_b32 v184, v128

; __device__ __forceinline__ unsigned cvt_pk_bf16(float lo, float hi) { unsigned r; asm volatile("v_cvt_pk_bf16_f32 %0, %1, %2" : "=v"(r) : "v"(lo), "v"(hi)); return r; }
; __device__ __forceinline__ float shx(float v, int o, int lane) { return __int_as_float(__builtin_amdgcn_ds_bpermute((lane ^ o) << 2, __float_as_int(v))); }
;     __device__ __forceinline__ void operator()(const f32x4 (&acc)[2][2][4][2], const Unit& u, int wr, int wc, int fr, int fq) const {
;         const int bidx = u.pm >> 4, row0 = u.pm * BM + wr * 64 + fr, col0 = u.pn * BM + wc * 32 + 4 * fq, lane = fq * 16 + fr;
;         f32x4 gv[2][2], gs[2][2];
; #pragma unroll
;         for (int bj = 0; bj < 2; ++bj)
; #pragma unroll
;             for (int n = 0; n < 2; ++n) { const int c = col0 + bj * HALF + n * 16; gv[bj][n] = *(const f32x4*)(gate + (size_t)bidx * NMOD + c);
;                 gs[bj][n] = *(const f32x4*)(gnext + c) * (*(const f32x4*)(scn + (size_t)bidx * NMOD + c) + 1.0f); }
; #pragma unroll
;         for (int ai = 0; ai < 2; ++ai)
; #pragma unroll
;             for (int m = 0; m < 4; ++m) { const int row = row0 + ai * HALF + m * 16; const size_t off = (size_t)row * DM + col0; float ss = 0.f;
; #pragma unroll
;                 for (int bj = 0; bj < 2; ++bj)
; #pragma unroll
;                     for (int n = 0; n < 2; ++n) { const f32x4 x = *(const f32x4*)(src + off + bj * HALF + n * 16) + gv[bj][n] * acc[ai][bj][m][n];
;                         *(f32x4*)(dst + off + bj * HALF + n * 16) = x; ss += (x[0] * x[0] + x[1] * x[1]) + (x[2] * x[2] + x[3] * x[3]);
;                         const f32x4 hh = x * gs[bj][n]; u32x2 w; w.x = cvt_pk_bf16(hh[0], hh[1]); w.y = cvt_pk_bf16(hh[2], hh[3]); *(u32x2*)(Hn + off + bj * HALF + n * 16) = w; }
;                 ss += shx(ss, 16, lane); ss += shx(ss, 32, lane);
;                 if (fq == 0) scr[(ai * HALF + wr * 64 + m * 16 + fr) * 4 + wc] = ss; }
.LBB0_1909:
	s_ashr_i32 s25, s34, 4
	s_lshl_b32 s34, s34, 8
	s_mul_hi_i32 s27, s25, 0x6000
	s_mulk_i32 s25, 0x6000
	v_lshl_or_b32 v168, s36, 8, v185
	s_add_u32 s36, s58, s25
	s_addc_u32 s37, s59, s27
	s_add_u32 s38, s60, s25
	v_ashrrev_i32_e32 v169, 31, v168
	s_addc_u32 s39, s61, s27
	v_lshlrev_b64 v[80:81], 2, v[168:169]
	v_lshl_add_u64 v[176:177], s[38:39], 0, v[80:81]
	v_lshl_add_u64 v[170:171], s[36:37], 0, v[80:81]
	v_lshl_add_u64 v[174:175], s[20:21], 0, v[80:81]
	global_load_dwordx4 v[80:83], v[176:177], off
	global_load_dwordx4 v[72:75], v[174:175], off
	global_load_dwordx4 v[92:95], v[170:171], off
	s_waitcnt vmcnt(0)
	v_pk_add_f32 v[82:83], v[82:83], 1.0 op_sel_hi:[1,0]
	v_pk_add_f32 v[80:81], v[80:81], 1.0 op_sel_hi:[1,0]
	v_pk_mul_f32 v[164:165], v[74:75], v[82:83]
	v_pk_mul_f32 v[166:167], v[72:73], v[80:81]
	global_load_dwordx4 v[88:91], v[170:171], off offset:64
	global_load_dwordx4 v[72:75], v[174:175], off offset:64
	global_load_dwordx4 v[80:83], v[176:177], off offset:64
	s_waitcnt vmcnt(0)
	v_pk_add_f32 v[82:83], v[82:83], 1.0 op_sel_hi:[1,0]
	v_pk_add_f32 v[80:81], v[80:81], 1.0 op_sel_hi:[1,0]
	v_pk_mul_f32 v[160:161], v[74:75], v[82:83]
	v_pk_mul_f32 v[162:163], v[72:73], v[80:81]
	global_load_dwordx4 v[80:83], v[170:171], off offset:512
	global_load_dwordx4 v[72:75], v[174:175], off offset:512
	global_load_dwordx4 v[152:155], v[176:177], off offset:512
	s_waitcnt vmcnt(0)
	v_pk_add_f32 v[154:155], v[154:155], 1.0 op_sel_hi:[1,0]
	v_pk_add_f32 v[152:153], v[152:153], 1.0 op_sel_hi:[1,0]
	v_pk_mul_f32 v[156:157], v[74:75], v[154:155]
	v_pk_mul_f32 v[158:159], v[72:73], v[152:153]
	global_load_dwordx4 v[72:75], v[170:171], off offset:576
	global_load_dwordx4 v[152:155], v[174:175], off offset:576
	s_nop 0
	global_load_dwordx4 v[174:177], v[176:177], off offset:576
	s_waitcnt vmcnt(0)
	v_pk_add_f32 v[170:171], v[176:177], 1.0 op_sel_hi:[1,0]
	s_nop 0
	v_pk_mul_f32 v[154:155], v[154:155], v[170:171]
	v_add_u32_e32 v170, s34, v180
	v_pk_add_f32 v[174:175], v[174:175], 1.0 op_sel_hi:[1,0]
	v_ashrrev_i32_e32 v171, 31, v170
	v_pk_mul_f32 v[152:153], v[152:153], v[174:175]
	v_lshlrev_b64 v[174:175], 10, v[170:171]
	v_lshl_add_u64 v[192:193], v[174:175], 0, v[168:169]
	v_lshl_add_u64 v[178:179], v[192:193], 2, s[16:17]
	v_lshlrev_b32_e32 v228, 2, v192
	v_mov_b32_e32 v229, v228
	global_load_dwordx4 v[196:199], v229, s[16:17]
	global_load_dwordx4 v[200:203], v229, s[16:17] offset:64
	global_load_dwordx4 v[204:207], v229, s[16:17] offset:512
	global_load_dwordx4 v[208:211], v229, s[16:17] offset:576
	v_add_u32_e32 v229, 0x10000, v228
	global_load_dwordx4 v[212:215], v229, s[16:17]
	global_load_dwordx4 v[216:219], v229, s[16:17] offset:64
	global_load_dwordx4 v[220:223], v229, s[16:17] offset:512
	global_load_dwordx4 v[224:227], v229, s[16:17] offset:576
	s_waitcnt vmcnt(7)
	v_pk_fma_f32 v[142:143], v[142:143], v[94:95], v[198:199]
	v_pk_fma_f32 v[140:141], v[140:141], v[92:93], v[196:197]
	v_mul_f32_e32 v175, v143, v143
	v_mul_f32_e32 v174, v141, v141
	global_store_dwordx4 v[178:179], v[140:143], off
	v_fmac_f32_e32 v174, v140, v140
	v_fmac_f32_e32 v175, v142, v142
	v_pk_mul_f32 v[140:141], v[166:167], v[140:141]
	v_add_f32_e32 v194, v174, v175
	v_cvt_pk_bf16_f32 v174, v140, v141
	v_lshl_add_u64 v[140:141], v[192:193], 1, s[14:15]
	v_pk_mul_f32 v[142:143], v[164:165], v[142:143]
	s_nop 0
	v_cvt_pk_bf16_f32 v175, v142, v143
	global_store_dwordx2 v[140:141], v[174:175], off
	s_waitcnt vmcnt(8)
	v_pk_fma_f32 v[136:137], v[136:137], v[88:89], v[200:201]
	v_pk_fma_f32 v[138:139], v[138:139], v[90:91], v[202:203]
	v_mul_f32_e32 v142, v137, v137
	global_store_dwordx4 v[178:179], v[136:139], off offset:64
	v_fmac_f32_e32 v142, v136, v136
	v_mul_f32_e32 v143, v139, v139
	v_pk_mul_f32 v[136:137], v[162:163], v[136:137]
	v_fmac_f32_e32 v143, v138, v138
	v_pk_mul_f32 v[138:139], v[160:161], v[138:139]
	v_cvt_pk_bf16_f32 v136, v136, v137
	v_add_f32_e32 v142, v142, v143
	v_cvt_pk_bf16_f32 v137, v138, v139
	global_store_dwordx2 v[140:141], v[136:137], off offset:32
	v_add_f32_e32 v142, v194, v142
	s_waitcnt vmcnt(9)
	v_pk_fma_f32 v[132:133], v[132:133], v[80:81], v[204:205]
	v_pk_fma_f32 v[134:135], v[134:135], v[82:83], v[206:207]
	v_mul_f32_e32 v136, v133, v133
	global_store_dwordx4 v[178:179], v[132:135], off offset:512
	v_fmac_f32_e32 v136, v132, v132
	v_mul_f32_e32 v137, v135, v135
	v_pk_mul_f32 v[132:133], v[158:159], v[132:133]
	v_fmac_f32_e32 v137, v134, v134
	v_pk_mul_f32 v[134:135], v[156:157], v[134:135]
	v_cvt_pk_bf16_f32 v132, v132, v133
	v_add_f32_e32 v136, v136, v137
	v_cvt_pk_bf16_f32 v133, v134, v135
	global_store_dwordx2 v[140:141], v[132:133], off offset:256
	v_add_f32_e32 v136, v142, v136
	s_waitcnt vmcnt(10)
	v_pk_fma_f32 v[130:131], v[130:131], v[74:75], v[210:211]
	v_pk_fma_f32 v[128:129], v[128:129], v[72:73], v[208:209]
	v_add_u32_e32 v229, 0x20000, v228
	global_load_dwordx4 v[196:199], v229, s[16:17]
	global_load_dwordx4 v[200:203], v229, s[16:17] offset:64
	global_load_dwordx4 v[204:207], v229, s[16:17] offset:512
	global_load_dwordx4 v[208:211], v229, s[16:17] offset:576
	v_mul_f32_e32 v133, v131, v131
	v_mul_f32_e32 v132, v129, v129
	v_fmac_f32_e32 v132, v128, v128
	v_fmac_f32_e32 v133, v130, v130
	global_store_dwordx4 v[178:179], v[128:131], off offset:576
	v_add_f32_e32 v132, v132, v133
	v_add_f32_e32 v132, v136, v132
	v_pk_mul_f32 v[128:129], v[152:153], v[128:129]
	v_pk_mul_f32 v[130:131], v[154:155], v[130:131]
	v_cvt_pk_bf16_f32 v128, v128, v129
	s_nop 0
	v_cvt_pk_bf16_f32 v129, v130, v131
	global_store_dwordx2 v[140:141], v[128:129], off offset:288
	ds_bpermute_b32 v128, v182, v132
	s_waitcnt lgkmcnt(0)
	v_add_f32_e32 v128, v132, v128
	ds_bpermute_b32 v129, v183, v128
	s_and_saveexec_b64 s[36:37], s[8:9]
	s_mov_b32 s70, 0xbf3a00e3
	s_cbranch_execz .LBB0_1911
	s_waitcnt lgkmcnt(0)
	v_add_f32_e32 v128, v128, v129
	ds_write_b32 v184, v128
; __device__ __forceinline__ unsigned cvt_pk_bf16(float lo, float hi) { unsigned r; asm volatile("v_cvt_pk_bf16_f32 %0, %1, %2" : "=v"(r) : "v"(lo), "v"(hi)); return r; }
; __device__ __forceinline__ float shx(float v, int o, int lane) { return __int_as_float(__builtin_amdgcn_ds_bpermute((lane ^ o) << 2, __float_as_int(v))); }
;     __device__ __forceinline__ void operator()(const f32x4 (&acc)[2][2][4][2], const Unit& u, int wr, int wc, int fr, int fq) const {
;     ...
;             for (int m = 0; m < 4; ++m) { const int row = row0 + ai * HALF + m * 16; const size_t off = (size_t)row * DM + col0; float ss = 0.f;
; #pragma unroll
;                 for (int bj = 0; bj < 2; ++bj)
; #pragma unroll
;                     for (int n = 0; n < 2; ++n) { const f32x4 x = *(const f32x4*)(src + off + bj * HALF + n * 16) + gv[bj][n] * acc[ai][bj][m][n];
;                         *(f32x4*)(dst + off + bj * HALF + n * 16) = x; ss += (x[0] * x[0] + x[1] * x[1]) + (x[2] * x[2] + x[3] * x[3]);
;                         const f32x4 hh = x * gs[bj][n]; u32x2 w; w.x = cvt_pk_bf16(hh[0], hh[1]); w.y = cvt_pk_bf16(hh[2], hh[3]); *(u32x2*)(Hn + off + bj * HALF + n * 16) = w; }
;                 ss += shx(ss, 16, lane); ss += shx(ss, 32, lane);
;                 if (fq == 0) scr[(ai * HALF + wr * 64 + m * 16 + fr) * 4 + wc] = ss; }
.LBB0_1911:
	s_or_b64 exec, exec, s[36:37]
	v_or_b32_e32 v128, 16, v170
	s_waitcnt lgkmcnt(0)
	v_ashrrev_i32_e32 v129, 31, v128
	v_lshlrev_b64 v[128:129], 10, v[128:129]
	v_lshl_add_u64 v[132:133], v[128:129], 0, v[168:169]
	v_lshl_add_u64 v[134:135], v[132:133], 2, s[16:17]
	v_lshl_add_u64 v[132:133], v[132:133], 1, s[14:15]
	s_waitcnt vmcnt(15)
	v_pk_fma_f32 v[124:125], v[124:125], v[92:93], v[212:213]
	v_pk_fma_f32 v[126:127], v[126:127], v[94:95], v[214:215]
	v_pk_mul_f32 v[130:131], v[166:167], v[124:125]
	global_store_dwordx4 v[134:135], v[124:127], off
	v_pk_mul_f32 v[128:129], v[164:165], v[126:127]
	v_cvt_pk_bf16_f32 v130, v130, v131
	s_nop 0
	v_cvt_pk_bf16_f32 v131, v128, v129
	global_store_dwordx2 v[132:133], v[130:131], off
	v_mul_f32_e32 v125, v125, v125
	v_mul_f32_e32 v127, v127, v127
	v_fmac_f32_e32 v125, v124, v124
	v_fmac_f32_e32 v127, v126, v126
	v_add_f32_e32 v124, v125, v127
	s_waitcnt vmcnt(16)
	v_pk_fma_f32 v[120:121], v[120:121], v[88:89], v[216:217]
	v_pk_fma_f32 v[122:123], v[122:123], v[90:91], v[218:219]
	v_pk_mul_f32 v[130:131], v[162:163], v[120:121]
	global_store_dwordx4 v[134:135], v[120:123], off offset:64
	v_pk_mul_f32 v[128:129], v[160:161], v[122:123]
	v_cvt_pk_bf16_f32 v130, v130, v131
	s_nop 0
	v_cvt_pk_bf16_f32 v131, v128, v129
	global_store_dwordx2 v[132:133], v[130:131], off offset:32
	v_mul_f32_e32 v121, v121, v121
	v_mul_f32_e32 v123, v123, v123
	v_fmac_f32_e32 v121, v120, v120
	v_fmac_f32_e32 v123, v122, v122
	v_add_f32_e32 v120, v121, v123
	v_add_f32_e32 v120, v124, v120
	s_waitcnt vmcnt(17)
	v_pk_fma_f32 v[116:117], v[116:117], v[80:81], v[220:221]
	v_pk_fma_f32 v[118:119], v[118:119], v[82:83], v[222:223]
	v_pk_mul_f32 v[130:131], v[158:159], v[116:117]
	global_store_dwordx4 v[134:135], v[116:119], off offset:512
	v_pk_mul_f32 v[128:129], v[156:157], v[118:119]
	v_cvt_pk_bf16_f32 v130, v130, v131
	s_nop 0
	v_cvt_pk_bf16_f32 v131, v128, v129
	global_store_dwordx2 v[132:133], v[130:131], off offset:256
	v_mul_f32_e32 v117, v117, v117
	v_mul_f32_e32 v119, v119, v119
	v_fmac_f32_e32 v117, v116, v116
	v_fmac_f32_e32 v119, v118, v118
	v_add_f32_e32 v116, v117, v119
	v_add_f32_e32 v118, v120, v116
	s_waitcnt vmcnt(18)
	v_pk_fma_f32 v[116:117], v[114:115], v[74:75], v[226:227]
	v_pk_fma_f32 v[114:115], v[112:113], v[72:73], v[224:225]
	v_add_u32_e32 v229, 0x30000, v228
	global_load_dwordx4 v[212:215], v229, s[16:17]
	global_load_dwordx4 v[216:219], v229, s[16:17] offset:64
	global_load_dwordx4 v[220:223], v229, s[16:17] offset:512
	global_load_dwordx4 v[224:227], v229, s[16:17] offset:576
	v_mul_f32_e32 v113, v117, v117
	v_mul_f32_e32 v112, v115, v115
	v_fmac_f32_e32 v112, v114, v114
	v_fmac_f32_e32 v113, v116, v116
	v_add_f32_e32 v112, v112, v113
	v_add_f32_e32 v112, v118, v112
	ds_bpermute_b32 v113, v182, v112
	global_store_dwordx4 v[134:135], v[114:117], off offset:576
	s_waitcnt lgkmcnt(0)
	v_add_f32_e32 v112, v112, v113
	ds_bpermute_b32 v113, v183, v112
	v_pk_mul_f32 v[114:115], v[152:153], v[114:115]
	v_pk_mul_f32 v[116:117], v[154:155], v[116:117]
	v_cvt_pk_bf16_f32 v114, v114, v115
	s_nop 0
	v_cvt_pk_bf16_f32 v115, v116, v117
	global_store_dwordx2 v[132:133], v[114:115], off offset:288
	s_and_saveexec_b64 s[36:37], s[8:9]
	s_cbranch_execz .LBB0_1913
	s_waitcnt lgkmcnt(0)
	v_add_f32_e32 v112, v112, v113
	ds_write_b32 v184, v112 offset:256
.LBB0_1913:
	s_or_b64 exec, exec, s[36:37]
	v_or_b32_e32 v112, 32, v170
	s_waitcnt lgkmcnt(0)
	v_ashrrev_i32_e32 v113, 31, v112
	v_lshlrev_b64 v[112:113], 10, v[112:113]
	v_lshl_add_u64 v[116:117], v[112:113], 0, v[168:169]
	v_lshl_add_u64 v[118:119], v[116:117], 2, s[16:17]
	v_lshl_add_u64 v[116:117], v[116:117], 1, s[14:15]
	s_waitcnt vmcnt(17)
	v_pk_fma_f32 v[108:109], v[108:109], v[92:93], v[196:197]
	v_pk_fma_f32 v[110:111], v[110:111], v[94:95], v[198:199]
	v_pk_mul_f32 v[114:115], v[166:167], v[108:109]
	global_store_dwordx4 v[118:119], v[108:111], off
	v_pk_mul_f32 v[112:113], v[164:165], v[110:111]
	v_cvt_pk_bf16_f32 v114, v114, v115
	s_nop 0
	v_cvt_pk_bf16_f32 v115, v112, v113
	global_store_dwordx2 v[116:117], v[114:115], off
	v_mul_f32_e32 v109, v109, v109
	v_mul_f32_e32 v111, v111, v111
	v_fmac_f32_e32 v109, v108, v108
	v_fmac_f32_e32 v111, v110, v110
	v_add_f32_e32 v108, v109, v111
	s_waitcnt vmcnt(18)
	v_pk_fma_f32 v[104:105], v[104:105], v[88:89], v[200:201]
	v_pk_fma_f32 v[106:107], v[106:107], v[90:91], v[202:203]
	v_pk_mul_f32 v[114:115], v[162:163], v[104:105]
	global_store_dwordx4 v[118:119], v[104:107], off offset:64
	v_pk_mul_f32 v[112:113], v[160:161], v[106:107]
	v_cvt_pk_bf16_f32 v114, v114, v115
	s_nop 0
	v_cvt_pk_bf16_f32 v115, v112, v113
	global_store_dwordx2 v[116:117], v[114:115], off offset:32
	v_mul_f32_e32 v105, v105, v105
	v_mul_f32_e32 v107, v107, v107
	v_fmac_f32_e32 v105, v104, v104
	v_fmac_f32_e32 v107, v106, v106
	v_add_f32_e32 v104, v105, v107
	v_add_f32_e32 v104, v108, v104
	s_waitcnt vmcnt(19)
	v_pk_fma_f32 v[100:101], v[100:101], v[80:81], v[204:205]
	v_pk_fma_f32 v[102:103], v[102:103], v[82:83], v[206:207]
	v_pk_mul_f32 v[114:115], v[158:159], v[100:101]
	global_store_dwordx4 v[118:119], v[100:103], off offset:512
	v_pk_mul_f32 v[112:113], v[156:157], v[102:103]
	v_cvt_pk_bf16_f32 v114, v114, v115
	s_nop 0
	v_cvt_pk_bf16_f32 v115, v112, v113
	global_store_dwordx2 v[116:117], v[114:115], off offset:256
	v_mul_f32_e32 v101, v101, v101
	v_mul_f32_e32 v103, v103, v103
	v_fmac_f32_e32 v101, v100, v100
	v_fmac_f32_e32 v103, v102, v102
	v_add_f32_e32 v100, v101, v103
	v_add_f32_e32 v102, v104, v100
	s_waitcnt vmcnt(20)
	v_pk_fma_f32 v[100:101], v[98:99], v[74:75], v[210:211]
	v_pk_fma_f32 v[98:99], v[96:97], v[72:73], v[208:209]
	v_add_u32_e32 v229, 0x80000, v228
	global_load_dwordx4 v[196:199], v229, s[16:17]
	global_load_dwordx4 v[200:203], v229, s[16:17] offset:64
	global_load_dwordx4 v[204:207], v229, s[16:17] offset:512
	global_load_dwordx4 v[208:211], v229, s[16:17] offset:576
	v_mul_f32_e32 v97, v101, v101
	v_mul_f32_e32 v96, v99, v99
	v_fmac_f32_e32 v96, v98, v98
	v_fmac_f32_e32 v97, v100, v100
	v_add_f32_e32 v96, v96, v97
	v_add_f32_e32 v96, v102, v96
	ds_bpermute_b32 v97, v182, v96
	global_store_dwordx4 v[118:119], v[98:101], off offset:576
	s_waitcnt lgkmcnt(0)
	v_add_f32_e32 v96, v96, v97
	ds_bpermute_b32 v97, v183, v96
	v_pk_mul_f32 v[98:99], v[152:153], v[98:99]
	v_pk_mul_f32 v[100:101], v[154:155], v[100:101]
	v_cvt_pk_bf16_f32 v98, v98, v99
	s_nop 0
	v_cvt_pk_bf16_f32 v99, v100, v101
	global_store_dwordx2 v[116:117], v[98:99], off offset:288
	s_and_saveexec_b64 s[36:37], s[8:9]
	s_cbranch_execz .LBB0_1915
	s_waitcnt lgkmcnt(0)
	v_add_f32_e32 v96, v96, v97
	ds_write_b32 v184, v96 offset:512
; __device__ __forceinline__ unsigned cvt_pk_bf16(float lo, float hi) { unsigned r; asm volatile("v_cvt_pk_bf16_f32 %0, %1, %2" : "=v"(r) : "v"(lo), "v"(hi)); return r; }
; __device__ __forceinline__ float shx(float v, int o, int lane) { return __int_as_float(__builtin_amdgcn_ds_bpermute((lane ^ o) << 2, __float_as_int(v))); }
;     __device__ __forceinline__ void operator()(const f32x4 (&acc)[2][2][4][2], const Unit& u, int wr, int wc, int fr, int fq) const {
;     ...
;             for (int m = 0; m < 4; ++m) { const int row = row0 + ai * HALF + m * 16; const size_t off = (size_t)row * DM + col0; float ss = 0.f;
; #pragma unroll
;                 for (int bj = 0; bj < 2; ++bj)
; #pragma unroll
;                     for (int n = 0; n < 2; ++n) { const f32x4 x = *(const f32x4*)(src + off + bj * HALF + n * 16) + gv[bj][n] * acc[ai][bj][m][n];
;                         *(f32x4*)(dst + off + bj * HALF + n * 16) = x; ss += (x[0] * x[0] + x[1] * x[1]) + (x[2] * x[2] + x[3] * x[3]);
;                         const f32x4 hh = x * gs[bj][n]; u32x2 w; w.x = cvt_pk_bf16(hh[0], hh[1]); w.y = cvt_pk_bf16(hh[2], hh[3]); *(u32x2*)(Hn + off + bj * HALF + n * 16) = w; }
;                 ss += shx(ss, 16, lane); ss += shx(ss, 32, lane);
;                 if (fq == 0) scr[(ai * HALF + wr * 64 + m * 16 + fr) * 4 + wc] = ss; }
.LBB0_1915:
	s_or_b64 exec, exec, s[36:37]
	v_or_b32_e32 v96, 48, v170
	s_waitcnt lgkmcnt(0)
	v_ashrrev_i32_e32 v97, 31, v96
	v_lshlrev_b64 v[96:97], 10, v[96:97]
	v_lshl_add_u64 v[100:101], v[96:97], 0, v[168:169]
	v_lshl_add_u64 v[102:103], v[100:101], 2, s[16:17]
	v_lshl_add_u64 v[100:101], v[100:101], 1, s[14:15]
	s_waitcnt vmcnt(17)
	v_pk_fma_f32 v[84:85], v[84:85], v[92:93], v[212:213]
	v_pk_fma_f32 v[86:87], v[86:87], v[94:95], v[214:215]
	v_pk_mul_f32 v[98:99], v[166:167], v[84:85]
	global_store_dwordx4 v[102:103], v[84:87], off
	v_pk_mul_f32 v[96:97], v[164:165], v[86:87]
	v_cvt_pk_bf16_f32 v98, v98, v99
	s_nop 0
	v_cvt_pk_bf16_f32 v99, v96, v97
	global_store_dwordx2 v[100:101], v[98:99], off
	v_mul_f32_e32 v85, v85, v85
	v_mul_f32_e32 v87, v87, v87
	v_fmac_f32_e32 v85, v84, v84
	v_fmac_f32_e32 v87, v86, v86
	v_add_f32_e32 v84, v85, v87
	s_waitcnt vmcnt(18)
	v_pk_fma_f32 v[76:77], v[76:77], v[88:89], v[216:217]
	v_pk_fma_f32 v[78:79], v[78:79], v[90:91], v[218:219]
	v_pk_mul_f32 v[98:99], v[162:163], v[76:77]
	global_store_dwordx4 v[102:103], v[76:79], off offset:64
	v_pk_mul_f32 v[96:97], v[160:161], v[78:79]
	v_cvt_pk_bf16_f32 v98, v98, v99
	s_nop 0
	v_cvt_pk_bf16_f32 v99, v96, v97
	global_store_dwordx2 v[100:101], v[98:99], off offset:32
	v_mul_f32_e32 v77, v77, v77
	v_mul_f32_e32 v79, v79, v79
	v_fmac_f32_e32 v77, v76, v76
	v_fmac_f32_e32 v79, v78, v78
	v_add_f32_e32 v76, v77, v79
	v_add_f32_e32 v76, v84, v76
	s_waitcnt vmcnt(19)
	v_pk_fma_f32 v[68:69], v[68:69], v[80:81], v[220:221]
	v_pk_fma_f32 v[70:71], v[70:71], v[82:83], v[222:223]
	v_pk_mul_f32 v[98:99], v[158:159], v[68:69]
	global_store_dwordx4 v[102:103], v[68:71], off offset:512
	v_pk_mul_f32 v[96:97], v[156:157], v[70:71]
	v_cvt_pk_bf16_f32 v98, v98, v99
	s_nop 0
	v_cvt_pk_bf16_f32 v99, v96, v97
	global_store_dwordx2 v[100:101], v[98:99], off offset:256
	v_mul_f32_e32 v69, v69, v69
	v_mul_f32_e32 v71, v71, v71
	v_fmac_f32_e32 v69, v68, v68
	v_fmac_f32_e32 v71, v70, v70
	v_add_f32_e32 v68, v69, v71
	v_add_f32_e32 v70, v76, v68
	s_waitcnt vmcnt(20)
	v_pk_fma_f32 v[68:69], v[66:67], v[74:75], v[226:227]
	v_pk_fma_f32 v[66:67], v[64:65], v[72:73], v[224:225]
	v_add_u32_e32 v229, 0x90000, v228
	global_load_dwordx4 v[212:215], v229, s[16:17]
	global_load_dwordx4 v[216:219], v229, s[16:17] offset:64
	global_load_dwordx4 v[220:223], v229, s[16:17] offset:512
	global_load_dwordx4 v[224:227], v229, s[16:17] offset:576
	v_mul_f32_e32 v65, v69, v69
	v_mul_f32_e32 v64, v67, v67
	v_fmac_f32_e32 v64, v66, v66
	v_fmac_f32_e32 v65, v68, v68
	v_add_f32_e32 v64, v64, v65
	v_add_f32_e32 v64, v70, v64
	ds_bpermute_b32 v65, v182, v64
	global_store_dwordx4 v[102:103], v[66:69], off offset:576
	s_waitcnt lgkmcnt(0)
	v_add_f32_e32 v64, v64, v65
	ds_bpermute_b32 v65, v183, v64
	v_pk_mul_f32 v[66:67], v[152:153], v[66:67]
	v_pk_mul_f32 v[68:69], v[154:155], v[68:69]
	v_cvt_pk_bf16_f32 v66, v66, v67
	s_nop 0
	v_cvt_pk_bf16_f32 v67, v68, v69
	global_store_dwordx2 v[100:101], v[66:67], off offset:288
	s_and_saveexec_b64 s[36:37], s[8:9]
	s_cbranch_execz .LBB0_1917
	s_waitcnt lgkmcnt(0)
	v_add_f32_e32 v64, v64, v65
	ds_write_b32 v184, v64 offset:768
.LBB0_1917:
	s_or_b64 exec, exec, s[36:37]
	s_waitcnt lgkmcnt(0)
	v_lshlrev_b64 v[64:65], 10, v[170:171]
	v_lshl_add_u64 v[64:65], v[64:65], 0, v[168:169]
	s_mov_b64 s[36:37], 0x20000
	v_lshl_add_u64 v[70:71], v[64:65], 0, s[36:37]
	v_lshl_add_u64 v[76:77], v[70:71], 2, s[16:17]
	v_lshl_add_u64 v[70:71], v[70:71], 1, s[14:15]
	s_waitcnt vmcnt(17)
	v_pk_fma_f32 v[60:61], v[60:61], v[92:93], v[196:197]
	v_pk_fma_f32 v[62:63], v[62:63], v[94:95], v[198:199]
	v_pk_mul_f32 v[68:69], v[166:167], v[60:61]
	global_store_dwordx4 v[76:77], v[60:63], off
	v_pk_mul_f32 v[66:67], v[164:165], v[62:63]
	v_cvt_pk_bf16_f32 v68, v68, v69
	s_nop 0
	v_cvt_pk_bf16_f32 v69, v66, v67
	global_store_dwordx2 v[70:71], v[68:69], off
	v_mul_f32_e32 v61, v61, v61
	v_mul_f32_e32 v63, v63, v63
	v_fmac_f32_e32 v61, v60, v60
	v_fmac_f32_e32 v63, v62, v62
	v_add_f32_e32 v60, v61, v63
	s_waitcnt vmcnt(18)
	v_pk_fma_f32 v[56:57], v[56:57], v[88:89], v[200:201]
	v_pk_fma_f32 v[58:59], v[58:59], v[90:91], v[202:203]
	v_pk_mul_f32 v[68:69], v[162:163], v[56:57]
	global_store_dwordx4 v[76:77], v[56:59], off offset:64
	v_pk_mul_f32 v[66:67], v[160:161], v[58:59]
	v_cvt_pk_bf16_f32 v68, v68, v69
	s_nop 0
	v_cvt_pk_bf16_f32 v69, v66, v67
	global_store_dwordx2 v[70:71], v[68:69], off offset:32
	v_mul_f32_e32 v57, v57, v57
	v_mul_f32_e32 v59, v59, v59
	v_fmac_f32_e32 v57, v56, v56
	v_fmac_f32_e32 v59, v58, v58
	v_add_f32_e32 v56, v57, v59
	v_add_f32_e32 v56, v60, v56
	s_waitcnt vmcnt(19)
	v_pk_fma_f32 v[52:53], v[52:53], v[80:81], v[204:205]
	v_pk_fma_f32 v[54:55], v[54:55], v[82:83], v[206:207]
	v_pk_mul_f32 v[68:69], v[158:159], v[52:53]
	global_store_dwordx4 v[76:77], v[52:55], off offset:512
	v_pk_mul_f32 v[66:67], v[156:157], v[54:55]
	v_cvt_pk_bf16_f32 v68, v68, v69
	s_nop 0
	v_cvt_pk_bf16_f32 v69, v66, v67
	global_store_dwordx2 v[70:71], v[68:69], off offset:256
	v_mul_f32_e32 v53, v53, v53
	v_mul_f32_e32 v55, v55, v55
	v_fmac_f32_e32 v53, v52, v52
	v_fmac_f32_e32 v55, v54, v54
	v_add_f32_e32 v52, v53, v55
	v_add_f32_e32 v54, v56, v52
	s_waitcnt vmcnt(20)
	v_pk_fma_f32 v[52:53], v[50:51], v[74:75], v[210:211]
	v_pk_fma_f32 v[50:51], v[48:49], v[72:73], v[208:209]
	v_add_u32_e32 v229, 0xa0000, v228
	global_load_dwordx4 v[196:199], v229, s[16:17]
	global_load_dwordx4 v[200:203], v229, s[16:17] offset:64
	global_load_dwordx4 v[204:207], v229, s[16:17] offset:512
	global_load_dwordx4 v[208:211], v229, s[16:17] offset:576
	v_mul_f32_e32 v49, v53, v53
	v_mul_f32_e32 v48, v51, v51
	v_fmac_f32_e32 v48, v50, v50
	v_fmac_f32_e32 v49, v52, v52
	v_add_f32_e32 v48, v48, v49
	v_add_f32_e32 v48, v54, v48
	ds_bpermute_b32 v49, v182, v48
	global_store_dwordx4 v[76:77], v[50:53], off offset:576
	s_waitcnt lgkmcnt(0)
	v_add_f32_e32 v48, v48, v49
	ds_bpermute_b32 v49, v183, v48
	v_pk_mul_f32 v[50:51], v[152:153], v[50:51]
	v_pk_mul_f32 v[52:53], v[154:155], v[52:53]
	v_cvt_pk_bf16_f32 v50, v50, v51
	s_nop 0
	v_cvt_pk_bf16_f32 v51, v52, v53
	global_store_dwordx2 v[70:71], v[50:51], off offset:288
	s_and_saveexec_b64 s[36:37], s[8:9]
	s_cbranch_execz .LBB0_1919
	s_waitcnt lgkmcnt(0)
	v_add_f32_e32 v48, v48, v49
	ds_write_b32 v184, v48 offset:2048
; __device__ __forceinline__ unsigned cvt_pk_bf16(float lo, float hi) { unsigned r; asm volatile("v_cvt_pk_bf16_f32 %0, %1, %2" : "=v"(r) : "v"(lo), "v"(hi)); return r; }
; __device__ __forceinline__ float shx(float v, int o, int lane) { return __int_as_float(__builtin_amdgcn_ds_bpermute((lane ^ o) << 2, __float_as_int(v))); }
;     __device__ __forceinline__ void operator()(const f32x4 (&acc)[2][2][4][2], const Unit& u, int wr, int wc, int fr, int fq) const {
;     ...
;             for (int m = 0; m < 4; ++m) { const int row = row0 + ai * HALF + m * 16; const size_t off = (size_t)row * DM + col0; float ss = 0.f;
; #pragma unroll
;                 for (int bj = 0; bj < 2; ++bj)
; #pragma unroll
;                     for (int n = 0; n < 2; ++n) { const f32x4 x = *(const f32x4*)(src + off + bj * HALF + n * 16) + gv[bj][n] * acc[ai][bj][m][n];
;                         *(f32x4*)(dst + off + bj * HALF + n * 16) = x; ss += (x[0] * x[0] + x[1] * x[1]) + (x[2] * x[2] + x[3] * x[3]);
;                         const f32x4 hh = x * gs[bj][n]; u32x2 w; w.x = cvt_pk_bf16(hh[0], hh[1]); w.y = cvt_pk_bf16(hh[2], hh[3]); *(u32x2*)(Hn + off + bj * HALF + n * 16) = w; }
;                 ss += shx(ss, 16, lane); ss += shx(ss, 32, lane);
;                 if (fq == 0) scr[(ai * HALF + wr * 64 + m * 16 + fr) * 4 + wc] = ss; }
.LBB0_1919:
	s_or_b64 exec, exec, s[36:37]
	s_mov_b64 s[36:37], 0x24000
	v_lshl_add_u64 v[52:53], v[64:65], 0, s[36:37]
	v_lshl_add_u64 v[54:55], v[52:53], 2, s[16:17]
	s_waitcnt lgkmcnt(0)
	v_lshl_add_u64 v[52:53], v[52:53], 1, s[14:15]
	s_waitcnt vmcnt(17)
	v_pk_fma_f32 v[44:45], v[44:45], v[92:93], v[212:213]
	v_pk_fma_f32 v[46:47], v[46:47], v[94:95], v[214:215]
	v_pk_mul_f32 v[50:51], v[166:167], v[44:45]
	global_store_dwordx4 v[54:55], v[44:47], off
	v_pk_mul_f32 v[48:49], v[164:165], v[46:47]
	v_cvt_pk_bf16_f32 v50, v50, v51
	s_nop 0
	v_cvt_pk_bf16_f32 v51, v48, v49
	global_store_dwordx2 v[52:53], v[50:51], off
	v_mul_f32_e32 v45, v45, v45
	v_mul_f32_e32 v47, v47, v47
	v_fmac_f32_e32 v45, v44, v44
	v_fmac_f32_e32 v47, v46, v46
	v_add_f32_e32 v44, v45, v47
	s_waitcnt vmcnt(18)
	v_pk_fma_f32 v[40:41], v[40:41], v[88:89], v[216:217]
	v_pk_fma_f32 v[42:43], v[42:43], v[90:91], v[218:219]
	v_pk_mul_f32 v[50:51], v[162:163], v[40:41]
	global_store_dwordx4 v[54:55], v[40:43], off offset:64
	v_pk_mul_f32 v[48:49], v[160:161], v[42:43]
	v_cvt_pk_bf16_f32 v50, v50, v51
	s_nop 0
	v_cvt_pk_bf16_f32 v51, v48, v49
	global_store_dwordx2 v[52:53], v[50:51], off offset:32
	v_mul_f32_e32 v41, v41, v41
	v_mul_f32_e32 v43, v43, v43
	v_fmac_f32_e32 v41, v40, v40
	v_fmac_f32_e32 v43, v42, v42
	v_add_f32_e32 v40, v41, v43
	v_add_f32_e32 v40, v44, v40
	s_waitcnt vmcnt(19)
	v_pk_fma_f32 v[36:37], v[36:37], v[80:81], v[220:221]
	v_pk_fma_f32 v[38:39], v[38:39], v[82:83], v[222:223]
	v_pk_mul_f32 v[50:51], v[158:159], v[36:37]
	global_store_dwordx4 v[54:55], v[36:39], off offset:512
	v_pk_mul_f32 v[48:49], v[156:157], v[38:39]
	v_cvt_pk_bf16_f32 v50, v50, v51
	s_nop 0
	v_cvt_pk_bf16_f32 v51, v48, v49
	global_store_dwordx2 v[52:53], v[50:51], off offset:256
	v_mul_f32_e32 v37, v37, v37
	v_mul_f32_e32 v39, v39, v39
	v_fmac_f32_e32 v37, v36, v36
	v_fmac_f32_e32 v39, v38, v38
	v_add_f32_e32 v36, v37, v39
	v_add_f32_e32 v38, v40, v36
	s_waitcnt vmcnt(20)
	v_pk_fma_f32 v[36:37], v[34:35], v[74:75], v[226:227]
	v_pk_fma_f32 v[34:35], v[32:33], v[72:73], v[224:225]
	v_add_u32_e32 v229, 0xb0000, v228
	global_load_dwordx4 v[212:215], v229, s[16:17]
	global_load_dwordx4 v[216:219], v229, s[16:17] offset:64
	global_load_dwordx4 v[220:223], v229, s[16:17] offset:512
	global_load_dwordx4 v[224:227], v229, s[16:17] offset:576
	v_mul_f32_e32 v33, v37, v37
	v_mul_f32_e32 v32, v35, v35
	v_fmac_f32_e32 v32, v34, v34
	v_fmac_f32_e32 v33, v36, v36
	v_add_f32_e32 v32, v32, v33
	v_add_f32_e32 v32, v38, v32
	ds_bpermute_b32 v33, v182, v32
	global_store_dwordx4 v[54:55], v[34:37], off offset:576
	s_waitcnt lgkmcnt(0)
	v_add_f32_e32 v32, v32, v33
	ds_bpermute_b32 v33, v183, v32
	v_pk_mul_f32 v[34:35], v[152:153], v[34:35]
	v_pk_mul_f32 v[36:37], v[154:155], v[36:37]
	v_cvt_pk_bf16_f32 v34, v34, v35
	s_nop 0
	v_cvt_pk_bf16_f32 v35, v36, v37
	global_store_dwordx2 v[52:53], v[34:35], off offset:288
	s_and_saveexec_b64 s[36:37], s[8:9]
	s_cbranch_execz .LBB0_1921
	s_waitcnt lgkmcnt(0)
	v_add_f32_e32 v32, v32, v33
	ds_write_b32 v184, v32 offset:2304
; __device__ __forceinline__ unsigned cvt_pk_bf16(float lo, float hi) { unsigned r; asm volatile("v_cvt_pk_bf16_f32 %0, %1, %2" : "=v"(r) : "v"(lo), "v"(hi)); return r; }
; __device__ __forceinline__ float shx(float v, int o, int lane) { return __int_as_float(__builtin_amdgcn_ds_bpermute((lane ^ o) << 2, __float_as_int(v))); }
;     __device__ __forceinline__ void operator()(const f32x4 (&acc)[2][2][4][2], const Unit& u, int wr, int wc, int fr, int fq) const {
;     ...
;             for (int m = 0; m < 4; ++m) { const int row = row0 + ai * HALF + m * 16; const size_t off = (size_t)row * DM + col0; float ss = 0.f;
; #pragma unroll
;                 for (int bj = 0; bj < 2; ++bj)
; #pragma unroll
;                     for (int n = 0; n < 2; ++n) { const f32x4 x = *(const f32x4*)(src + off + bj * HALF + n * 16) + gv[bj][n] * acc[ai][bj][m][n];
;                         *(f32x4*)(dst + off + bj * HALF + n * 16) = x; ss += (x[0] * x[0] + x[1] * x[1]) + (x[2] * x[2] + x[3] * x[3]);
;                         const f32x4 hh = x * gs[bj][n]; u32x2 w; w.x = cvt_pk_bf16(hh[0], hh[1]); w.y = cvt_pk_bf16(hh[2], hh[3]); *(u32x2*)(Hn + off + bj * HALF + n * 16) = w; }
;                 ss += shx(ss, 16, lane); ss += shx(ss, 32, lane);
;                 if (fq == 0) scr[(ai * HALF + wr * 64 + m * 16 + fr) * 4 + wc] = ss; }
.LBB0_1921:
	s_or_b64 exec, exec, s[36:37]
	s_waitcnt lgkmcnt(0)
	v_lshlrev_b64 v[32:33], 10, v[170:171]
	v_lshl_add_u64 v[32:33], v[32:33], 0, v[168:169]
	s_mov_b64 s[36:37], 0x28000
	v_lshl_add_u64 v[38:39], v[32:33], 0, s[36:37]
	v_lshl_add_u64 v[40:41], v[38:39], 2, s[16:17]
	v_lshl_add_u64 v[38:39], v[38:39], 1, s[14:15]
	s_waitcnt vmcnt(17)
	v_pk_fma_f32 v[28:29], v[28:29], v[92:93], v[196:197]
	v_pk_fma_f32 v[30:31], v[30:31], v[94:95], v[198:199]
	v_pk_mul_f32 v[36:37], v[166:167], v[28:29]
	global_store_dwordx4 v[40:41], v[28:31], off
	v_pk_mul_f32 v[34:35], v[164:165], v[30:31]
	v_cvt_pk_bf16_f32 v36, v36, v37
	s_nop 0
	v_cvt_pk_bf16_f32 v37, v34, v35
	global_store_dwordx2 v[38:39], v[36:37], off
	v_mul_f32_e32 v29, v29, v29
	v_mul_f32_e32 v31, v31, v31
	v_fmac_f32_e32 v29, v28, v28
	v_fmac_f32_e32 v31, v30, v30
	v_add_f32_e32 v28, v29, v31
	s_waitcnt vmcnt(18)
	v_pk_fma_f32 v[24:25], v[24:25], v[88:89], v[200:201]
	v_pk_fma_f32 v[26:27], v[26:27], v[90:91], v[202:203]
	v_pk_mul_f32 v[36:37], v[162:163], v[24:25]
	global_store_dwordx4 v[40:41], v[24:27], off offset:64
	v_pk_mul_f32 v[34:35], v[160:161], v[26:27]
	v_cvt_pk_bf16_f32 v36, v36, v37
	s_nop 0
	v_cvt_pk_bf16_f32 v37, v34, v35
	global_store_dwordx2 v[38:39], v[36:37], off offset:32
	v_mul_f32_e32 v25, v25, v25
	v_mul_f32_e32 v27, v27, v27
	v_fmac_f32_e32 v25, v24, v24
	v_fmac_f32_e32 v27, v26, v26
	v_add_f32_e32 v24, v25, v27
	v_add_f32_e32 v24, v28, v24
	s_waitcnt vmcnt(19)
	v_pk_fma_f32 v[20:21], v[20:21], v[80:81], v[204:205]
	v_pk_fma_f32 v[22:23], v[22:23], v[82:83], v[206:207]
	v_pk_mul_f32 v[36:37], v[158:159], v[20:21]
	global_store_dwordx4 v[40:41], v[20:23], off offset:512
	v_pk_mul_f32 v[34:35], v[156:157], v[22:23]
	v_cvt_pk_bf16_f32 v36, v36, v37
	s_nop 0
	v_cvt_pk_bf16_f32 v37, v34, v35
	global_store_dwordx2 v[38:39], v[36:37], off offset:256
	v_mul_f32_e32 v21, v21, v21
	v_mul_f32_e32 v23, v23, v23
	v_fmac_f32_e32 v21, v20, v20
	v_fmac_f32_e32 v23, v22, v22
	v_add_f32_e32 v20, v21, v23
	v_add_f32_e32 v22, v24, v20
	s_waitcnt vmcnt(20)
	v_pk_fma_f32 v[20:21], v[18:19], v[74:75], v[210:211]
	v_pk_fma_f32 v[18:19], v[16:17], v[72:73], v[208:209]
	v_mul_f32_e32 v17, v21, v21
	v_mul_f32_e32 v16, v19, v19
	v_fmac_f32_e32 v16, v18, v18
	v_fmac_f32_e32 v17, v20, v20
	v_add_f32_e32 v16, v16, v17
	v_add_f32_e32 v16, v22, v16
	ds_bpermute_b32 v17, v182, v16
	global_store_dwordx4 v[40:41], v[18:21], off offset:576
	s_waitcnt lgkmcnt(0)
	v_add_f32_e32 v16, v16, v17
	ds_bpermute_b32 v17, v183, v16
	v_pk_mul_f32 v[18:19], v[152:153], v[18:19]
	v_pk_mul_f32 v[20:21], v[154:155], v[20:21]
	v_cvt_pk_bf16_f32 v18, v18, v19
	s_nop 0
	v_cvt_pk_bf16_f32 v19, v20, v21
	global_store_dwordx2 v[38:39], v[18:19], off offset:288
	s_and_saveexec_b64 s[36:37], s[8:9]
	s_cbranch_execz .LBB0_1923
	s_waitcnt lgkmcnt(0)
	v_add_f32_e32 v16, v16, v17
	ds_write_b32 v184, v16 offset:2560
.LBB0_1923:
	s_or_b64 exec, exec, s[36:37]
	s_mov_b64 s[36:37], 0x2c000
	v_lshl_add_u64 v[20:21], v[32:33], 0, s[36:37]
	v_lshl_add_u64 v[22:23], v[20:21], 2, s[16:17]
	s_waitcnt lgkmcnt(0)
	v_lshl_add_u64 v[20:21], v[20:21], 1, s[14:15]
	s_waitcnt vmcnt(13)
	v_pk_fma_f32 v[12:13], v[12:13], v[92:93], v[212:213]
	v_pk_fma_f32 v[14:15], v[14:15], v[94:95], v[214:215]
	v_pk_mul_f32 v[18:19], v[166:167], v[12:13]
	global_store_dwordx4 v[22:23], v[12:15], off
	v_pk_mul_f32 v[16:17], v[164:165], v[14:15]
	v_cvt_pk_bf16_f32 v18, v18, v19
	s_nop 0
	v_cvt_pk_bf16_f32 v19, v16, v17
	global_store_dwordx2 v[20:21], v[18:19], off
	v_mul_f32_e32 v13, v13, v13
	v_mul_f32_e32 v15, v15, v15
	v_fmac_f32_e32 v13, v12, v12
	v_fmac_f32_e32 v15, v14, v14
	v_add_f32_e32 v12, v13, v15
	s_waitcnt vmcnt(14)
	v_pk_fma_f32 v[8:9], v[8:9], v[88:89], v[216:217]
	v_pk_fma_f32 v[10:11], v[10:11], v[90:91], v[218:219]
	v_pk_mul_f32 v[18:19], v[162:163], v[8:9]
	global_store_dwordx4 v[22:23], v[8:11], off offset:64
	v_pk_mul_f32 v[16:17], v[160:161], v[10:11]
	v_cvt_pk_bf16_f32 v18, v18, v19
	s_nop 0
	v_cvt_pk_bf16_f32 v19, v16, v17
	global_store_dwordx2 v[20:21], v[18:19], off offset:32
	v_mul_f32_e32 v9, v9, v9
	v_mul_f32_e32 v11, v11, v11
	v_fmac_f32_e32 v9, v8, v8
	v_fmac_f32_e32 v11, v10, v10
	v_add_f32_e32 v8, v9, v11
	v_add_f32_e32 v8, v12, v8
	s_waitcnt vmcnt(15)
	v_pk_fma_f32 v[4:5], v[4:5], v[80:81], v[220:221]
	v_pk_fma_f32 v[6:7], v[6:7], v[82:83], v[222:223]
	v_pk_mul_f32 v[18:19], v[158:159], v[4:5]
	global_store_dwordx4 v[22:23], v[4:7], off offset:512
	v_pk_mul_f32 v[16:17], v[156:157], v[6:7]
	v_cvt_pk_bf16_f32 v18, v18, v19
	s_nop 0
	v_cvt_pk_bf16_f32 v19, v16, v17
	global_store_dwordx2 v[20:21], v[18:19], off offset:256
	v_mul_f32_e32 v5, v5, v5
	v_mul_f32_e32 v7, v7, v7
	v_fmac_f32_e32 v5, v4, v4
	v_fmac_f32_e32 v7, v6, v6
	v_add_f32_e32 v4, v5, v7
	v_add_f32_e32 v6, v8, v4
	s_waitcnt vmcnt(16)
	v_pk_fma_f32 v[4:5], v[2:3], v[74:75], v[226:227]
	v_pk_fma_f32 v[2:3], v[0:1], v[72:73], v[224:225]
	v_mul_f32_e32 v1, v5, v5
	v_mul_f32_e32 v0, v3, v3
	v_fmac_f32_e32 v0, v2, v2
	v_fmac_f32_e32 v1, v4, v4
	v_add_f32_e32 v0, v0, v1
	v_add_f32_e32 v0, v6, v0
	ds_bpermute_b32 v1, v182, v0
	global_store_dwordx4 v[22:23], v[2:5], off offset:576
	s_waitcnt lgkmcnt(0)
	v_add_f32_e32 v0, v0, v1
	ds_bpermute_b32 v1, v183, v0
	v_pk_mul_f32 v[2:3], v[152:153], v[2:3]
	v_pk_mul_f32 v[4:5], v[154:155], v[4:5]
	v_cvt_pk_bf16_f32 v2, v2, v3
	s_nop 0
	v_cvt_pk_bf16_f32 v3, v4, v5
	global_store_dwordx2 v[20:21], v[2:3], off offset:288
	s_and_saveexec_b64 s[36:37], s[8:9]
	s_cbranch_execz .LBB0_1925
	s_waitcnt lgkmcnt(0)
	v_add_f32_e32 v0, v0, v1
	ds_write_b32 v184, v0 offset:2816
